# int8 quantisation epilogues of the phase-5 and phase-13 GEMMs: scale multiply and rounding-constant add fused into one fma, clamp moved after the add (two VALU ops per element instead of three)
# baseline (speedup 1.0000x reference)
; #define PG8_STAGE(bufoff, gbase, voff) do { _Pragma("unroll") for (int _i = 0; _i < 2; ++_i) \
;         __builtin_amdgcn_global_load_lds((const unsigned*)((const char*)(gbase) + (voff)[_i]), (LAS unsigned*)(lds + (bufoff) + ldsw + _i * 8192), 16, 0, 0); } while (0)
; #define PG8_WAIT_V(n) asm volatile("s_waitcnt vmcnt(" #n ")" ::: "memory")
; #define PG8_BAR __builtin_amdgcn_s_barrier()
;     ...
;     for (int i = 0; i < 2; ++i) { int R, C; stage_rc(tid * 16 + i * 8192, R, C); const int Rb = Epi::PERM ? ((R & ~31) + perm32(R & 31)) : R;
;         voffA[i] = (unsigned)(R * K + C) * 2u; voffB[i] = (unsigned)(Rb * K + C) * 2u; }
;     const size_t kstep = (size_t)(BK * 2);
;     const size_t hstep = (size_t)HALF * K * 2;
;     const size_t tstep = 2 * hstep;
;     const unsigned ldsw = (unsigned)wid * 1024u;
;     const int aoff = lds_byte(wr * 64 + fr, fq * 8), boff = lds_byte(wc * 32 + fr, fq * 8);
;     ...
;     Unit cur, nxt; int ui = 0;
;     if (!S.next(0, cur)) return;
;     const int sc1_ = 0x7F7F7F7F; (void)sc1_;
;     f32x4 acc[2][2][4][2];
; #pragma unroll
;     for (int a = 0; a < 2; ++a)
; #pragma unroll
;         for (int b = 0; b < 2; ++b)
; #pragma unroll
;             for (int m = 0; m < 4; ++m)
; #pragma unroll
;                 for (int n = 0; n < 2; ++n) acc[a][b][m][n] = (f32x4){0.f, 0.f, 0.f, 0.f};
;     bf16x8 At[4][2], B0[2][2], B1[2][2];
;     const char* cA = (const char*)g.A + (size_t)cur.pm * tstep + (size_t)cur.kt0 * kstep; const char* cB = (const char*)g.Bt + (size_t)cur.e * g.estride + (size_t)cur.pn * tstep + (size_t)cur.kt0 * kstep;
;     PG8_STAGE(PG8_SB(0, 0), cB, voffB); PG8_STAGE(PG8_SB(0, 1), cB + hstep, voffB); PG8_STAGE(PG8_SA(0, 0), cA, voffA); PG8_STAGE(PG8_SA(0, 1), cA + hstep, voffA);
;     if (wr == 1) PG8_BAR;
;     PG8_WAIT_V(2); PG8_BAR;
;     PG8_STAGE(PG8_SB(1, 0), cB + kstep, voffB); PG8_STAGE(PG8_SA(1, 0), cA + kstep, voffA); PG8_STAGE(PG8_SB(1, 1), cB + hstep + kstep, voffB);
;     PG8_WAIT_V(6); PG8_BAR;
.LBB0_3844:
	s_add_u32 s18, s56, 0x43000000
	s_addc_u32 s19, s57, 0
	s_add_u32 s20, s56, 0x5f000000
	s_addc_u32 s21, s57, 0
	s_lshl_b32 s3, s3, 5
	s_mov_b64 s[24:25], 0x80
	s_and_b32 s7, s3, 0x60
	s_add_i32 m0, s37, 0x18000
	v_lshl_add_u64 v[6:7], v[6:7], 0, s[24:25]
	s_lshl_b32 s5, s2, 13
	s_lshl_b32 s3, s7, 7
	s_waitcnt vmcnt(2)
	s_barrier
	global_load_lds_dwordx4 v[6:7], off
	v_lshl_add_u64 v[4:5], v[4:5], 0, s[24:25]
	s_add_i32 m0, s37, 0x1a000
	s_add_i32 s55, s37, 0x8000
	s_add_i32 s58, s37, 0xa000
	global_load_lds_dwordx4 v[4:5], off
	v_lshl_add_u64 v[0:1], v[0:1], 0, s[24:25]
	s_mov_b32 m0, s55
	s_add_u32 s26, s46, 0xb0080
	global_load_lds_dwordx4 v[0:1], off
	v_lshl_add_u64 v[0:1], v[2:3], 0, s[24:25]
	s_mov_b32 m0, s58
	s_addc_u32 s27, s47, 0
	global_load_lds_dwordx4 v[0:1], off
	s_add_i32 m0, s37, 0x1c000
	v_lshl_add_u64 v[0:1], s[26:27], 0, v[162:163]
	global_load_lds_dwordx4 v[0:1], off
	v_lshl_add_u64 v[0:1], s[26:27], 0, v[166:167]
	s_add_i32 m0, s37, 0x1e000
	s_cmpk_lt_u32 s6, 0x100
	global_load_lds_dwordx4 v[0:1], off
	v_bfe_u32 v1, v8, 4, 2
	v_and_b32_e32 v0, 15, v8
	v_lshlrev_b32_e32 v2, 4, v1
	v_lshl_or_b32 v186, s2, 6, v0
	v_lshl_or_b32 v0, v0, 6, v2
	v_lshlrev_b32_e32 v2, 2, v8
	v_and_b32_e32 v2, 32, v2
	v_bitop3_b32 v3, v0, s5, v2 bitop3:0xde
	v_bitop3_b32 v187, s3, v0, v2 bitop3:0xf6
	v_cmp_eq_u32_e64 s[2:3], 0, v1
	v_lshl_or_b32 v188, v1, 3, s7
	v_lshrrev_b32_e32 v1, 1, v9
	v_mul_lo_u32 v0, v11, s4
	s_mov_b32 s5, 0xb000
	v_mad_u64_u32 v[0:1], s[6:7], v1, s5, v[0:1]
	v_or_b32_e32 v0, v0, v10
	s_mov_b64 s[40:41], 0xb0080
	v_add_lshl_u32 v0, v0, v12, 1
	v_mov_b32_e32 v1, v163
	v_lshl_add_u64 v[168:169], v[0:1], 0, s[40:41]
	v_lshrrev_b32_e32 v1, 1, v13
	v_mul_lo_u32 v0, v14, s4
	v_mad_u64_u32 v[0:1], s[4:5], v1, s5, v[0:1]
	v_or_b32_e32 v0, v0, v15
	s_waitcnt vmcnt(6)
	v_add_lshl_u32 v0, v0, v16, 1
	v_mov_b32_e32 v1, v163
	s_cselect_b64 s[26:27], -1, 0
	v_lshl_add_u64 v[170:171], v[0:1], 0, s[40:41]
	s_add_i32 s61, 0, 0x10000
	s_add_i32 s62, 0, 0x14000
	v_mbcnt_lo_u32_b32 v0, -1, 0
	s_ashr_i32 s59, s33, 31
	s_ashr_i32 s60, s22, 31
	v_mov_b64_e32 v[172:173], 0x200
	v_mov_b64_e32 v[174:175], 0x1ff
	v_add_u32_e32 v189, s61, v187
	v_add_u32_e32 v190, s62, v187
	v_add_u32_e32 v191, 0, v3
	v_mov_b32_e32 v192, 0x7f7f7f7f
	v_mbcnt_hi_u32_b32 v193, -1, v0
	s_mov_b32 s28, 0x3a000000
	s_mov_b32 s63, 0xf800000
	v_mov_b32_e32 v194, 0x260
	s_mov_b32 s30, 0x3fb504f3
	s_mov_b32 s36, 0x38800000
	s_mov_b32 s38, 0x41980000
	s_mov_b32 s64, 0xc2fe0000
	s_mov_b32 s65, 0xc0c0400
	s_mov_b32 s66, 0x4000c0c
	v_mov_b32_e32 v195, 0x42fe0000
	v_mov_b32_e32 v252, 0x4b400000
	v_mov_b32_e32 v253, 0x4b40007f
	s_mov_b32 s32, 0x4b3fff81
	s_barrier
	s_branch .LBB0_3847

;     __device__ __forceinline__ void operator()(EPI_ARGS) const {
;         const int row0 = u.pm * BM + wr * 64 + fr, col0 = u.pn * BM + wc * 32 + 8 * fq;
;         f32x4 gg[2][2], bb[2][2];
;         if constexpr (RESLN) {
; #pragma unroll
;             for (int bj = 0; bj < 2; ++bj)
; #pragma unroll
;                 for (int n = 0; n < 2; ++n) { gg[bj][n] = *(const f32x4*)(lg + col0 + bj * HALF + 4 * n); bb[bj][n] = *(const f32x4*)(lb + col0 + bj * HALF + 4 * n); } }
; #pragma unroll
;         for (int ai = 0; ai < 2; ++ai)
; #pragma unroll
;             for (int m = 0; m < 4; ++m) { const int row = row0 + ai * HALF + m * 16; const size_t off = (size_t)row * DM + col0;
;                 float mu = 0.f, rs = 1.f; if constexpr (RESLN) ln_stats(stin, row, mu, rs);
;                 float ss = 0.f, qq = 0.f;
; #pragma unroll
;                 for (int bj = 0; bj < 2; ++bj) { f32x4 r0 = __builtin_nontemporal_load((const f32x4*)(res + off + bj * HALF)), r1 = __builtin_nontemporal_load((const f32x4*)(res + off + bj * HALF + 4));
;                     if constexpr (RESLN) { r0 = (r0 - mu) * rs * gg[bj][0] + bb[bj][0]; r1 = (r1 - mu) * rs * gg[bj][1] + bb[bj][1]; }
;                     const f32x4 y0 = r0 * DN_ALPHA + acc[ai][bj][m][0] * ascale, y1 = r1 * DN_ALPHA + acc[ai][bj][m][1] * ascale;
;                     if constexpr (COPY != 4) { __builtin_nontemporal_store(y0, (f32x4*)(Y + off + bj * HALF)); __builtin_nontemporal_store(y1, (f32x4*)(Y + off + bj * HALF + 4)); }
;                     if constexpr (STATS) { ss += ((y0[0] + y0[1]) + (y0[2] + y0[3])) + ((y1[0] + y1[1]) + (y1[2] + y1[3]));
;                         qq += ((y0[0] * y0[0] + y0[1] * y0[1]) + (y0[2] * y0[2] + y0[3] * y0[3])) + ((y1[0] * y1[0] + y1[1] * y1[1]) + (y1[2] * y1[2] + y1[3] * y1[3])); }
;                     if constexpr (COPY == 1) *(u32x2*)((unsigned char*)copy + off + bj * HALF) = pack8fp8(y0 * cscale, y1 * cscale);
;                     if constexpr (COPY == 3) *(u32x2*)((unsigned char*)copy + off + bj * HALF) = pack8i8(y0 * cscale, y1 * cscale);
;                     if constexpr (COPY == 2 || COPY == 4) *(u32x4*)((bf16_t*)copy + off + bj * HALF) = pack8bf(y0, y1); }
;                 if constexpr (STATS) { ss += __shfl_xor(ss, 16); ss += __shfl_xor(ss, 32); qq += __shfl_xor(qq, 16); qq += __shfl_xor(qq, 32);
.LBB0_3861:
	v_lshl_add_u32 v178, s69, 8, v186
	v_lshl_or_b32 v176, s70, 8, v188
	v_ashrrev_i32_e32 v179, 31, v178
	v_ashrrev_i32_e32 v177, 31, v176
	v_lshlrev_b64 v[0:1], 11, v[178:179]
	v_lshlrev_b64 v[180:181], 3, v[178:179]
	v_lshl_add_u64 v[184:185], v[0:1], 0, v[176:177]
	v_lshl_add_u64 v[0:1], s[14:15], 0, v[180:181]
	global_load_dwordx2 v[204:205], v[0:1], off
	v_lshl_add_u64 v[182:183], v[184:185], 2, s[18:19]
	global_load_dwordx4 v[196:199], v[182:183], off nt
	global_load_dwordx4 v[200:203], v[182:183], off offset:16 nt
	global_load_dwordx4 v[228:231], v[182:183], off offset:512 nt
	global_load_dwordx4 v[232:235], v[182:183], off offset:528 nt
	v_lshlrev_b64 v[0:1], 2, v[176:177]
	v_lshl_add_u64 v[4:5], s[8:9], 0, v[0:1]
	v_lshl_add_u64 v[12:13], s[10:11], 0, v[0:1]
	global_load_dwordx4 v[16:19], v[12:13], off
	global_load_dwordx4 v[28:31], v[4:5], off
	global_load_dwordx4 v[20:23], v[4:5], off offset:16
	global_load_dwordx4 v[24:27], v[12:13], off offset:16
	global_load_dwordx4 v[0:3], v[4:5], off offset:528
	global_load_dwordx4 v[8:11], v[4:5], off offset:512
	s_nop 0
	global_load_dwordx4 v[4:7], v[12:13], off offset:528
	s_nop 0
	global_load_dwordx4 v[12:15], v[12:13], off offset:512
	v_lshl_add_u64 v[184:185], s[20:21], 0, v[184:185]
	s_waitcnt vmcnt(0)
	v_pk_mul_f32 v[208:209], v[204:205], s[28:29] op_sel_hi:[1,0]
	s_nop 0
	v_fma_f32 v179, -v208, v208, v209
	v_add_f32_e32 v179, 0x3727c5ac, v179
	v_rsq_f32_e32 v254, v179
	v_sub_f32_e32 v199, v199, v208
	v_sub_f32_e32 v198, v198, v208
	v_sub_f32_e32 v197, v197, v208
	v_sub_f32_e32 v196, v196, v208
	v_sub_f32_e32 v203, v203, v208
	v_sub_f32_e32 v202, v202, v208
	v_sub_f32_e32 v201, v201, v208
	v_sub_f32_e32 v200, v200, v208
	s_nop 0
	s_nop 1
	v_mov_b32_e32 v210, v254
	v_pk_mul_f32 v[196:197], v[196:197], v[210:211] op_sel_hi:[1,0]
	v_pk_mul_f32 v[198:199], v[198:199], v[210:211] op_sel_hi:[1,0]
	v_pk_mul_f32 v[200:201], v[200:201], v[210:211] op_sel_hi:[1,0]
	v_pk_mul_f32 v[202:203], v[202:203], v[210:211] op_sel_hi:[1,0]
	v_pk_fma_f32 v[198:199], v[30:31], v[198:199], v[18:19]
	v_pk_fma_f32 v[196:197], v[28:29], v[196:197], v[16:17]
	v_pk_fma_f32 v[202:203], v[22:23], v[202:203], v[26:27]
	v_pk_fma_f32 v[200:201], v[20:21], v[200:201], v[24:25]
	v_pk_mul_f32 v[196:197], v[196:197], s[30:31] op_sel_hi:[1,0]
	v_pk_mul_f32 v[198:199], v[198:199], s[30:31] op_sel_hi:[1,0]
	v_pk_mul_f32 v[200:201], v[200:201], s[30:31] op_sel_hi:[1,0]
	v_pk_mul_f32 v[202:203], v[202:203], s[30:31] op_sel_hi:[1,0]
	v_pk_fma_f32 v[158:159], v[158:159], s[36:37], v[198:199] op_sel_hi:[1,0,1]
	v_pk_fma_f32 v[156:157], v[156:157], s[36:37], v[196:197] op_sel_hi:[1,0,1]
	v_pk_fma_f32 v[198:199], v[154:155], s[36:37], v[202:203] op_sel_hi:[1,0,1]
	v_pk_fma_f32 v[196:197], v[152:153], s[36:37], v[200:201] op_sel_hi:[1,0,1]
	v_fmamk_f32 v152, v158, 0x41980000, v252
	v_fmamk_f32 v153, v159, 0x41980000, v252
	v_fmamk_f32 v154, v156, 0x41980000, v252
	v_fmamk_f32 v155, v157, 0x41980000, v252
	v_fmamk_f32 v200, v198, 0x41980000, v252
	v_fmamk_f32 v201, v199, 0x41980000, v252
	v_fmamk_f32 v202, v196, 0x41980000, v252
	v_fmamk_f32 v203, v197, 0x41980000, v252
	v_med3_f32 v154, v154, s32, v253
	v_med3_f32 v155, v155, s32, v253
	v_med3_f32 v152, v152, s32, v253
	v_med3_f32 v153, v153, s32, v253
	v_med3_f32 v179, v202, s32, v253
	v_med3_f32 v202, v203, s32, v253
	v_med3_f32 v200, v200, s32, v253
	v_med3_f32 v201, v201, s32, v253
	v_perm_b32 v154, v155, v154, s65
	v_perm_b32 v152, v153, v152, s66
	v_perm_b32 v153, v202, v179, s65
	v_perm_b32 v155, v201, v200, s66
	v_or_b32_e32 v152, v154, v152
	v_or_b32_e32 v153, v153, v155
	global_store_dwordx4 v[182:183], v[156:159], off nt
	global_store_dwordx4 v[182:183], v[196:199], off offset:16 nt
	global_store_dwordx2 v[184:185], v[152:153], off
	s_waitcnt vmcnt(11)
	s_nop 1
	v_mov_b32_e32 v200, v228
	v_mov_b32_e32 v201, v229
	v_mov_b32_e32 v202, v230
	v_mov_b32_e32 v203, v231
	v_mov_b32_e32 v204, v232
	v_mov_b32_e32 v205, v233
	v_mov_b32_e32 v206, v234
	v_mov_b32_e32 v207, v235
	v_and_b32_e32 v153, 64, v193
	v_xor_b32_e32 v152, 16, v193
	v_add_u32_e32 v153, 64, v153
	v_xor_b32_e32 v154, 32, v193
	v_cmp_lt_i32_e32 vcc, v152, v153
	v_add_f32_e32 v155, v158, v159
	v_add_f32_e32 v179, v196, v197
	v_cndmask_b32_e32 v152, v193, v152, vcc
	v_cmp_lt_i32_e32 vcc, v154, v153
	v_lshlrev_b32_e32 v153, 2, v152
	v_add_f32_e32 v209, v198, v199
	v_cndmask_b32_e32 v154, v193, v154, vcc
	v_lshlrev_b32_e32 v152, 2, v154
	v_add_f32_e32 v154, v156, v157
	v_mul_f32_e32 v157, v157, v157
	v_mul_f32_e32 v159, v159, v159
	v_mul_f32_e32 v197, v197, v197
	v_mul_f32_e32 v199, v199, v199
	v_add_f32_e32 v154, v154, v155
	v_add_f32_e32 v155, v179, v209
	v_fmac_f32_e32 v157, v156, v156
	v_fmac_f32_e32 v159, v158, v158
	v_fmac_f32_e32 v197, v196, v196
	v_fmac_f32_e32 v199, v198, v198
	v_add_f32_e32 v154, v154, v155
	v_add_f32_e32 v155, v157, v159
	v_add_f32_e32 v156, v197, v199
	v_add_f32_e32 v179, 0, v154
	v_add_f32_e32 v198, v155, v156
	v_sub_f32_e32 v155, v203, v208
	v_sub_f32_e32 v154, v202, v208
	v_sub_f32_e32 v157, v201, v208
	v_sub_f32_e32 v156, v200, v208
	v_sub_f32_e32 v159, v207, v208
	v_sub_f32_e32 v158, v206, v208
	v_sub_f32_e32 v197, v205, v208
	v_sub_f32_e32 v196, v204, v208
	v_pk_mul_f32 v[156:157], v[156:157], v[210:211] op_sel_hi:[1,0]
	v_pk_mul_f32 v[154:155], v[154:155], v[210:211] op_sel_hi:[1,0]
	v_pk_mul_f32 v[196:197], v[196:197], v[210:211] op_sel_hi:[1,0]
	v_pk_mul_f32 v[158:159], v[158:159], v[210:211] op_sel_hi:[1,0]
	v_pk_fma_f32 v[154:155], v[10:11], v[154:155], v[14:15]
	v_pk_fma_f32 v[156:157], v[8:9], v[156:157], v[12:13]
	v_pk_fma_f32 v[158:159], v[2:3], v[158:159], v[6:7]
; __device__ __forceinline__ u32x2 pack8i8(const f32x4 a, const f32x4 b) { return (u32x2){pack4i8(a), pack4i8(b)}; }
; __device__ __forceinline__ unsigned pack4i8(const f32x4 t) {
;     const float M = 12582912.f; const unsigned a = __float_as_uint(__builtin_amdgcn_fmed3f(t[0], -127.f, 127.f) + M), b = __float_as_uint(__builtin_amdgcn_fmed3f(t[1], -127.f, 127.f) + M),
;     __device__ __forceinline__ void operator()(EPI_ARGS) const {
;     ...
;             for (int m = 0; m < 4; ++m) { const int row = row0 + ai * HALF + m * 16; const size_t off = (size_t)row * DM + col0;
;                 float mu = 0.f, rs = 1.f; if constexpr (RESLN) ln_stats(stin, row, mu, rs);
;                 float ss = 0.f, qq = 0.f;
; #pragma unroll
;                 for (int bj = 0; bj < 2; ++bj) { f32x4 r0 = __builtin_nontemporal_load((const f32x4*)(res + off + bj * HALF)), r1 = __builtin_nontemporal_load((const f32x4*)(res + off + bj * HALF + 4));
;                     if constexpr (RESLN) { r0 = (r0 - mu) * rs * gg[bj][0] + bb[bj][0]; r1 = (r1 - mu) * rs * gg[bj][1] + bb[bj][1]; }
;                     const f32x4 y0 = r0 * DN_ALPHA + acc[ai][bj][m][0] * ascale, y1 = r1 * DN_ALPHA + acc[ai][bj][m][1] * ascale;
;                     if constexpr (COPY != 4) { __builtin_nontemporal_store(y0, (f32x4*)(Y + off + bj * HALF)); __builtin_nontemporal_store(y1, (f32x4*)(Y + off + bj * HALF + 4)); }
;                     if constexpr (STATS) { ss += ((y0[0] + y0[1]) + (y0[2] + y0[3])) + ((y1[0] + y1[1]) + (y1[2] + y1[3]));
;                         qq += ((y0[0] * y0[0] + y0[1] * y0[1]) + (y0[2] * y0[2] + y0[3] * y0[3])) + ((y1[0] * y1[0] + y1[1] * y1[1]) + (y1[2] * y1[2] + y1[3] * y1[3])); }
;                     if constexpr (COPY == 1) *(u32x2*)((unsigned char*)copy + off + bj * HALF) = pack8fp8(y0 * cscale, y1 * cscale);
;                     if constexpr (COPY == 3) *(u32x2*)((unsigned char*)copy + off + bj * HALF) = pack8i8(y0 * cscale, y1 * cscale);
;                     if constexpr (COPY == 2 || COPY == 4) *(u32x4*)((bf16_t*)copy + off + bj * HALF) = pack8bf(y0, y1); }
;                 if constexpr (STATS) { ss += __shfl_xor(ss, 16); ss += __shfl_xor(ss, 32); qq += __shfl_xor(qq, 16); qq += __shfl_xor(qq, 32);
;                     if (fq == 0) { unsafeAtomicAdd(stout + 2 * (size_t)row, ss); unsafeAtomicAdd(stout + 2 * (size_t)row + 1, qq); } }
	v_pk_fma_f32 v[196:197], v[0:1], v[196:197], v[4:5]
	v_pk_mul_f32 v[156:157], v[156:157], s[30:31] op_sel_hi:[1,0]
	v_pk_mul_f32 v[154:155], v[154:155], s[30:31] op_sel_hi:[1,0]
	v_pk_mul_f32 v[196:197], v[196:197], s[30:31] op_sel_hi:[1,0]
	v_pk_mul_f32 v[158:159], v[158:159], s[30:31] op_sel_hi:[1,0]
	v_pk_fma_f32 v[150:151], v[150:151], s[36:37], v[154:155] op_sel_hi:[1,0,1]
	v_pk_fma_f32 v[148:149], v[148:149], s[36:37], v[156:157] op_sel_hi:[1,0,1]
	v_pk_fma_f32 v[146:147], v[146:147], s[36:37], v[158:159] op_sel_hi:[1,0,1]
	v_pk_fma_f32 v[144:145], v[144:145], s[36:37], v[196:197] op_sel_hi:[1,0,1]
	v_add_f32_e32 v196, v148, v149
	v_add_f32_e32 v197, v150, v151
	v_add_f32_e32 v199, v144, v145
	v_add_f32_e32 v200, v146, v147
	v_mul_f32_e32 v201, v149, v149
	v_mul_f32_e32 v202, v151, v151
	v_mul_f32_e32 v203, v145, v145
	v_mul_f32_e32 v204, v147, v147
	global_store_dwordx4 v[182:183], v[148:151], off offset:512 nt
	global_store_dwordx4 v[182:183], v[144:147], off offset:528 nt
	v_fmamk_f32 v156, v148, 0x41980000, v252
	v_fmamk_f32 v157, v149, 0x41980000, v252
	v_fmamk_f32 v158, v146, 0x41980000, v252
	v_fmamk_f32 v159, v147, 0x41980000, v252
	v_fmamk_f32 v182, v144, 0x41980000, v252
	v_fmamk_f32 v183, v145, 0x41980000, v252
	v_add_f32_e32 v145, v196, v197
	v_add_f32_e32 v147, v199, v200
	v_fmac_f32_e32 v201, v148, v148
	v_fmac_f32_e32 v202, v150, v150
	v_fmac_f32_e32 v203, v144, v144
	v_fmac_f32_e32 v204, v146, v146
	v_med3_f32 v144, v156, s32, v253
	v_add_f32_e32 v145, v145, v147
	v_add_f32_e32 v147, v201, v202
	v_add_f32_e32 v156, v203, v204
	v_med3_f32 v146, v157, s32, v253
	v_add_f32_e32 v147, v147, v156
	v_add_f32_e32 v145, v145, v179
	v_add_f32_e32 v147, v198, v147
	v_perm_b32 v144, v146, v144, s65
	v_mov_b32_e32 v146, v145
	s_nop 1
	v_permlane16_swap_b32_e32 v145, v146
	v_mov_b32_e32 v156, v147
	s_nop 1
	v_permlane16_swap_b32_e32 v147, v156
	v_fmamk_f32 v154, v150, 0x41980000, v252
	v_fmamk_f32 v155, v151, 0x41980000, v252
	v_med3_f32 v150, v182, s32, v253
	v_med3_f32 v148, v154, s32, v253
	v_med3_f32 v149, v155, s32, v253
	v_perm_b32 v148, v149, v148, s66
	v_or_b32_e32 v148, v144, v148
	s_waitcnt lgkmcnt(0)
	v_add_f32_e32 v144, v145, v146
	s_waitcnt lgkmcnt(0)
	v_add_f32_e32 v146, v147, v156
	v_mov_b32_e32 v145, v144
	s_nop 1
	v_permlane32_swap_b32_e32 v144, v145
	v_mov_b32_e32 v147, v146
	s_nop 1
	v_permlane32_swap_b32_e32 v146, v147
	v_med3_f32 v151, v183, s32, v253
	v_med3_f32 v154, v158, s32, v253
	v_med3_f32 v155, v159, s32, v253
	v_perm_b32 v149, v151, v150, s65
	v_perm_b32 v150, v155, v154, s66
	v_or_b32_e32 v149, v149, v150
	global_store_dwordx2 v[184:185], v[148:149], off offset:128
	s_and_saveexec_b64 s[6:7], s[2:3]
	s_cbranch_execz .LBB0_3863
	v_lshl_add_u64 v[148:149], s[12:13], 0, v[180:181]
	s_waitcnt lgkmcnt(0)
	v_add_f32_e32 v144, v144, v145
	s_waitcnt lgkmcnt(0)
	v_add_f32_e32 v145, v146, v147
	global_atomic_add_f32 v[148:149], v144, off
	global_atomic_add_f32 v[148:149], v145, off offset:4
.LBB0_3863:
	s_or_b64 exec, exec, s[6:7]
	v_or_b32_e32 v144, 16, v178
	s_waitcnt lgkmcnt(1)
	v_ashrrev_i32_e32 v145, 31, v144
	s_waitcnt lgkmcnt(0)
	v_lshlrev_b64 v[146:147], 11, v[144:145]
	v_lshlrev_b64 v[144:145], 3, v[144:145]
	v_lshl_add_u64 v[158:159], v[146:147], 0, v[176:177]
	v_lshl_add_u64 v[146:147], s[14:15], 0, v[144:145]
	global_load_dwordx2 v[180:181], v[146:147], off
	v_lshl_add_u64 v[146:147], v[158:159], 2, s[18:19]
	global_load_dwordx4 v[148:151], v[146:147], off nt
	global_load_dwordx4 v[154:157], v[146:147], off offset:16 nt
	global_load_dwordx4 v[228:231], v[146:147], off offset:512 nt
	global_load_dwordx4 v[232:235], v[146:147], off offset:528 nt
	v_lshl_add_u64 v[158:159], s[20:21], 0, v[158:159]
	s_waitcnt vmcnt(4)
	v_pk_mul_f32 v[180:181], v[180:181], s[28:29] op_sel_hi:[1,0]
	s_nop 0
	v_fma_f32 v179, -v180, v180, v181
	v_add_f32_e32 v179, 0x3727c5ac, v179
	v_rsq_f32_e32 v254, v179
	s_waitcnt vmcnt(3)
	v_sub_f32_e32 v151, v151, v180
	v_sub_f32_e32 v150, v150, v180
	v_sub_f32_e32 v149, v149, v180
	v_sub_f32_e32 v148, v148, v180
	s_waitcnt vmcnt(2)
	v_sub_f32_e32 v157, v157, v180
	v_sub_f32_e32 v156, v156, v180
	v_sub_f32_e32 v155, v155, v180
	v_sub_f32_e32 v154, v154, v180
	s_nop 0
	s_nop 1
	v_mov_b32_e32 v182, v254
	v_pk_mul_f32 v[148:149], v[148:149], v[182:183] op_sel_hi:[1,0]
	v_pk_mul_f32 v[150:151], v[150:151], v[182:183] op_sel_hi:[1,0]
	v_pk_mul_f32 v[154:155], v[154:155], v[182:183] op_sel_hi:[1,0]
	v_pk_mul_f32 v[156:157], v[156:157], v[182:183] op_sel_hi:[1,0]
	v_pk_fma_f32 v[150:151], v[30:31], v[150:151], v[18:19]
	v_pk_fma_f32 v[148:149], v[28:29], v[148:149], v[16:17]
	v_pk_fma_f32 v[156:157], v[22:23], v[156:157], v[26:27]
	v_pk_fma_f32 v[154:155], v[20:21], v[154:155], v[24:25]
	v_pk_mul_f32 v[148:149], v[148:149], s[30:31] op_sel_hi:[1,0]
	v_pk_mul_f32 v[150:151], v[150:151], s[30:31] op_sel_hi:[1,0]
	v_pk_mul_f32 v[154:155], v[154:155], s[30:31] op_sel_hi:[1,0]
	v_pk_mul_f32 v[156:157], v[156:157], s[30:31] op_sel_hi:[1,0]
	v_pk_fma_f32 v[142:143], v[142:143], s[36:37], v[150:151] op_sel_hi:[1,0,1]
	v_pk_fma_f32 v[140:141], v[140:141], s[36:37], v[148:149] op_sel_hi:[1,0,1]
	v_pk_fma_f32 v[138:139], v[138:139], s[36:37], v[156:157] op_sel_hi:[1,0,1]
	v_pk_fma_f32 v[136:137], v[136:137], s[36:37], v[154:155] op_sel_hi:[1,0,1]
	v_fmamk_f32 v148, v142, 0x41980000, v252
	v_fmamk_f32 v149, v143, 0x41980000, v252
	v_fmamk_f32 v150, v140, 0x41980000, v252
	v_fmamk_f32 v151, v141, 0x41980000, v252
	v_fmamk_f32 v154, v138, 0x41980000, v252
	v_fmamk_f32 v155, v139, 0x41980000, v252
	v_fmamk_f32 v156, v136, 0x41980000, v252
	v_fmamk_f32 v157, v137, 0x41980000, v252
	v_med3_f32 v150, v150, s32, v253
	v_med3_f32 v151, v151, s32, v253
	v_med3_f32 v148, v148, s32, v253
	v_med3_f32 v149, v149, s32, v253
	v_med3_f32 v156, v156, s32, v253
	v_med3_f32 v157, v157, s32, v253
	v_med3_f32 v154, v154, s32, v253
	v_med3_f32 v155, v155, s32, v253
	v_perm_b32 v150, v151, v150, s65
	v_perm_b32 v148, v149, v148, s66
	v_perm_b32 v149, v157, v156, s65
	v_perm_b32 v151, v155, v154, s66
	v_or_b32_e32 v148, v150, v148
	v_or_b32_e32 v149, v149, v151
	global_store_dwordx4 v[146:147], v[140:143], off nt
	global_store_dwordx4 v[146:147], v[136:139], off offset:16 nt
	global_store_dwordx2 v[158:159], v[148:149], off
	s_waitcnt vmcnt(3)
; __device__ __forceinline__ u32x2 pack8i8(const f32x4 a, const f32x4 b) { return (u32x2){pack4i8(a), pack4i8(b)}; }
; __device__ __forceinline__ unsigned pack4i8(const f32x4 t) {
;     const float M = 12582912.f; const unsigned a = __float_as_uint(__builtin_amdgcn_fmed3f(t[0], -127.f, 127.f) + M), b = __float_as_uint(__builtin_amdgcn_fmed3f(t[1], -127.f, 127.f) + M),
;     __device__ __forceinline__ void operator()(EPI_ARGS) const {
;     ...
;             for (int m = 0; m < 4; ++m) { const int row = row0 + ai * HALF + m * 16; const size_t off = (size_t)row * DM + col0;
;                 float mu = 0.f, rs = 1.f; if constexpr (RESLN) ln_stats(stin, row, mu, rs);
;                 float ss = 0.f, qq = 0.f;
; #pragma unroll
;                 for (int bj = 0; bj < 2; ++bj) { f32x4 r0 = __builtin_nontemporal_load((const f32x4*)(res + off + bj * HALF)), r1 = __builtin_nontemporal_load((const f32x4*)(res + off + bj * HALF + 4));
;                     if constexpr (RESLN) { r0 = (r0 - mu) * rs * gg[bj][0] + bb[bj][0]; r1 = (r1 - mu) * rs * gg[bj][1] + bb[bj][1]; }
;                     const f32x4 y0 = r0 * DN_ALPHA + acc[ai][bj][m][0] * ascale, y1 = r1 * DN_ALPHA + acc[ai][bj][m][1] * ascale;
;                     if constexpr (COPY != 4) { __builtin_nontemporal_store(y0, (f32x4*)(Y + off + bj * HALF)); __builtin_nontemporal_store(y1, (f32x4*)(Y + off + bj * HALF + 4)); }
;                     if constexpr (STATS) { ss += ((y0[0] + y0[1]) + (y0[2] + y0[3])) + ((y1[0] + y1[1]) + (y1[2] + y1[3]));
;                         qq += ((y0[0] * y0[0] + y0[1] * y0[1]) + (y0[2] * y0[2] + y0[3] * y0[3])) + ((y1[0] * y1[0] + y1[1] * y1[1]) + (y1[2] * y1[2] + y1[3] * y1[3])); }
;                     if constexpr (COPY == 1) *(u32x2*)((unsigned char*)copy + off + bj * HALF) = pack8fp8(y0 * cscale, y1 * cscale);
;                     if constexpr (COPY == 3) *(u32x2*)((unsigned char*)copy + off + bj * HALF) = pack8i8(y0 * cscale, y1 * cscale);
;                     if constexpr (COPY == 2 || COPY == 4) *(u32x4*)((bf16_t*)copy + off + bj * HALF) = pack8bf(y0, y1); }
;                 if constexpr (STATS) { ss += __shfl_xor(ss, 16); ss += __shfl_xor(ss, 32); qq += __shfl_xor(qq, 16); qq += __shfl_xor(qq, 32);
;                     if (fq == 0) { unsafeAtomicAdd(stout + 2 * (size_t)row, ss); unsafeAtomicAdd(stout + 2 * (size_t)row + 1, qq); } }
	s_nop 1
	v_mov_b32_e32 v148, v228
	v_mov_b32_e32 v149, v229
	v_mov_b32_e32 v150, v230
	v_mov_b32_e32 v151, v231
	v_mov_b32_e32 v154, v232
	v_mov_b32_e32 v155, v233
	v_mov_b32_e32 v156, v234
	v_mov_b32_e32 v157, v235
	v_add_f32_e32 v179, v140, v141
	v_add_f32_e32 v181, v142, v143
	v_add_f32_e32 v183, v136, v137
	v_add_f32_e32 v184, v138, v139
	v_mul_f32_e32 v141, v141, v141
	v_mul_f32_e32 v143, v143, v143
	v_mul_f32_e32 v137, v137, v137
	v_mul_f32_e32 v139, v139, v139
	v_add_f32_e32 v179, v179, v181
	v_add_f32_e32 v181, v183, v184
	v_fmac_f32_e32 v141, v140, v140
	v_fmac_f32_e32 v143, v142, v142
	v_fmac_f32_e32 v137, v136, v136
	v_fmac_f32_e32 v139, v138, v138
	v_add_f32_e32 v136, v179, v181
	v_add_f32_e32 v138, v141, v143
	v_add_f32_e32 v137, v137, v139
	v_add_f32_e32 v179, 0, v136
	v_add_f32_e32 v181, v138, v137
	v_sub_f32_e32 v137, v151, v180
	v_sub_f32_e32 v136, v150, v180
	v_sub_f32_e32 v139, v149, v180
	v_sub_f32_e32 v138, v148, v180
	v_sub_f32_e32 v141, v157, v180
	v_sub_f32_e32 v140, v156, v180
	v_sub_f32_e32 v143, v155, v180
	v_sub_f32_e32 v142, v154, v180
	v_pk_mul_f32 v[138:139], v[138:139], v[182:183] op_sel_hi:[1,0]
	v_pk_mul_f32 v[136:137], v[136:137], v[182:183] op_sel_hi:[1,0]
	v_pk_mul_f32 v[142:143], v[142:143], v[182:183] op_sel_hi:[1,0]
	v_pk_mul_f32 v[140:141], v[140:141], v[182:183] op_sel_hi:[1,0]
	v_pk_fma_f32 v[136:137], v[10:11], v[136:137], v[14:15]
	v_pk_fma_f32 v[138:139], v[8:9], v[138:139], v[12:13]
	v_pk_fma_f32 v[140:141], v[2:3], v[140:141], v[6:7]
	v_pk_fma_f32 v[142:143], v[0:1], v[142:143], v[4:5]
	v_pk_mul_f32 v[138:139], v[138:139], s[30:31] op_sel_hi:[1,0]
	v_pk_mul_f32 v[136:137], v[136:137], s[30:31] op_sel_hi:[1,0]
	v_pk_mul_f32 v[142:143], v[142:143], s[30:31] op_sel_hi:[1,0]
	v_pk_mul_f32 v[140:141], v[140:141], s[30:31] op_sel_hi:[1,0]
	v_pk_fma_f32 v[134:135], v[134:135], s[36:37], v[136:137] op_sel_hi:[1,0,1]
	v_pk_fma_f32 v[132:133], v[132:133], s[36:37], v[138:139] op_sel_hi:[1,0,1]
	v_pk_fma_f32 v[130:131], v[130:131], s[36:37], v[140:141] op_sel_hi:[1,0,1]
	v_pk_fma_f32 v[128:129], v[128:129], s[36:37], v[142:143] op_sel_hi:[1,0,1]
	global_store_dwordx4 v[146:147], v[132:135], off offset:512 nt
	global_store_dwordx4 v[146:147], v[128:131], off offset:528 nt
	v_add_f32_e32 v146, v132, v133
	v_add_f32_e32 v147, v134, v135
	v_add_f32_e32 v148, v128, v129
	v_add_f32_e32 v149, v130, v131
	v_mul_f32_e32 v150, v133, v133
	v_mul_f32_e32 v151, v135, v135
	v_mul_f32_e32 v154, v129, v129
	v_mul_f32_e32 v155, v131, v131
	v_fmamk_f32 v138, v132, 0x41980000, v252
	v_fmamk_f32 v139, v133, 0x41980000, v252
	v_fmamk_f32 v140, v130, 0x41980000, v252
	v_fmamk_f32 v141, v131, 0x41980000, v252
	v_fmamk_f32 v142, v128, 0x41980000, v252
	v_fmamk_f32 v143, v129, 0x41980000, v252
	v_add_f32_e32 v129, v146, v147
	v_add_f32_e32 v131, v148, v149
	v_fmac_f32_e32 v150, v132, v132
	v_fmac_f32_e32 v151, v134, v134
	v_fmac_f32_e32 v154, v128, v128
	v_fmac_f32_e32 v155, v130, v130
	v_med3_f32 v128, v138, s32, v253
	v_add_f32_e32 v129, v129, v131
	v_add_f32_e32 v131, v150, v151
	v_add_f32_e32 v138, v154, v155
	v_med3_f32 v130, v139, s32, v253
	v_add_f32_e32 v131, v131, v138
	v_add_f32_e32 v129, v129, v179
	v_add_f32_e32 v131, v181, v131
	v_perm_b32 v128, v130, v128, s65
	v_mov_b32_e32 v130, v129
	s_nop 1
	v_permlane16_swap_b32_e32 v129, v130
	v_mov_b32_e32 v138, v131
	s_nop 1
	v_permlane16_swap_b32_e32 v131, v138
	v_fmamk_f32 v136, v134, 0x41980000, v252
	v_fmamk_f32 v137, v135, 0x41980000, v252
	v_med3_f32 v134, v142, s32, v253
	v_med3_f32 v132, v136, s32, v253
	v_med3_f32 v133, v137, s32, v253
	v_perm_b32 v132, v133, v132, s66
	v_or_b32_e32 v132, v128, v132
	s_waitcnt lgkmcnt(0)
	v_add_f32_e32 v128, v129, v130
	s_waitcnt lgkmcnt(0)
	v_add_f32_e32 v130, v131, v138
	v_mov_b32_e32 v129, v128
	s_nop 1
	v_permlane32_swap_b32_e32 v128, v129
	v_mov_b32_e32 v131, v130
	s_nop 1
	v_permlane32_swap_b32_e32 v130, v131
	v_med3_f32 v135, v143, s32, v253
	v_med3_f32 v136, v140, s32, v253
	v_med3_f32 v137, v141, s32, v253
	v_perm_b32 v133, v135, v134, s65
	v_perm_b32 v134, v137, v136, s66
	v_or_b32_e32 v133, v133, v134
	global_store_dwordx2 v[158:159], v[132:133], off offset:128
	s_and_saveexec_b64 s[6:7], s[2:3]
	s_cbranch_execz .LBB0_3865
	v_lshl_add_u64 v[132:133], s[12:13], 0, v[144:145]
	s_waitcnt lgkmcnt(0)
	v_add_f32_e32 v128, v128, v129
	s_waitcnt lgkmcnt(0)
	v_add_f32_e32 v129, v130, v131
	global_atomic_add_f32 v[132:133], v128, off
	global_atomic_add_f32 v[132:133], v129, off offset:4
; __device__ __forceinline__ u32x2 pack8i8(const f32x4 a, const f32x4 b) { return (u32x2){pack4i8(a), pack4i8(b)}; }
; __device__ __forceinline__ unsigned pack4i8(const f32x4 t) {
;     const float M = 12582912.f; const unsigned a = __float_as_uint(__builtin_amdgcn_fmed3f(t[0], -127.f, 127.f) + M), b = __float_as_uint(__builtin_amdgcn_fmed3f(t[1], -127.f, 127.f) + M),
;     __device__ __forceinline__ void operator()(EPI_ARGS) const {
;     ...
;             for (int m = 0; m < 4; ++m) { const int row = row0 + ai * HALF + m * 16; const size_t off = (size_t)row * DM + col0;
;                 float mu = 0.f, rs = 1.f; if constexpr (RESLN) ln_stats(stin, row, mu, rs);
;                 float ss = 0.f, qq = 0.f;
; #pragma unroll
;                 for (int bj = 0; bj < 2; ++bj) { f32x4 r0 = __builtin_nontemporal_load((const f32x4*)(res + off + bj * HALF)), r1 = __builtin_nontemporal_load((const f32x4*)(res + off + bj * HALF + 4));
;                     if constexpr (RESLN) { r0 = (r0 - mu) * rs * gg[bj][0] + bb[bj][0]; r1 = (r1 - mu) * rs * gg[bj][1] + bb[bj][1]; }
;                     const f32x4 y0 = r0 * DN_ALPHA + acc[ai][bj][m][0] * ascale, y1 = r1 * DN_ALPHA + acc[ai][bj][m][1] * ascale;
;                     if constexpr (COPY != 4) { __builtin_nontemporal_store(y0, (f32x4*)(Y + off + bj * HALF)); __builtin_nontemporal_store(y1, (f32x4*)(Y + off + bj * HALF + 4)); }
;                     if constexpr (STATS) { ss += ((y0[0] + y0[1]) + (y0[2] + y0[3])) + ((y1[0] + y1[1]) + (y1[2] + y1[3]));
;                         qq += ((y0[0] * y0[0] + y0[1] * y0[1]) + (y0[2] * y0[2] + y0[3] * y0[3])) + ((y1[0] * y1[0] + y1[1] * y1[1]) + (y1[2] * y1[2] + y1[3] * y1[3])); }
;                     if constexpr (COPY == 1) *(u32x2*)((unsigned char*)copy + off + bj * HALF) = pack8fp8(y0 * cscale, y1 * cscale);
;                     if constexpr (COPY == 3) *(u32x2*)((unsigned char*)copy + off + bj * HALF) = pack8i8(y0 * cscale, y1 * cscale);
;                     if constexpr (COPY == 2 || COPY == 4) *(u32x4*)((bf16_t*)copy + off + bj * HALF) = pack8bf(y0, y1); }
;                 if constexpr (STATS) { ss += __shfl_xor(ss, 16); ss += __shfl_xor(ss, 32); qq += __shfl_xor(qq, 16); qq += __shfl_xor(qq, 32);
;                     if (fq == 0) { unsafeAtomicAdd(stout + 2 * (size_t)row, ss); unsafeAtomicAdd(stout + 2 * (size_t)row + 1, qq); } }
.LBB0_3865:
	s_or_b64 exec, exec, s[6:7]
	v_or_b32_e32 v128, 32, v178
	s_waitcnt lgkmcnt(1)
	v_ashrrev_i32_e32 v129, 31, v128
	s_waitcnt lgkmcnt(0)
	v_lshlrev_b64 v[130:131], 11, v[128:129]
	v_lshlrev_b64 v[128:129], 3, v[128:129]
	v_lshl_add_u64 v[140:141], v[130:131], 0, v[176:177]
	v_lshl_add_u64 v[130:131], s[14:15], 0, v[128:129]
	global_load_dwordx2 v[142:143], v[130:131], off
	v_lshl_add_u64 v[130:131], v[140:141], 2, s[18:19]
	global_load_dwordx4 v[132:135], v[130:131], off nt
	global_load_dwordx4 v[136:139], v[130:131], off offset:16 nt
	global_load_dwordx4 v[228:231], v[130:131], off offset:512 nt
	global_load_dwordx4 v[232:235], v[130:131], off offset:528 nt
	v_lshl_add_u64 v[140:141], s[20:21], 0, v[140:141]
	s_waitcnt vmcnt(4)
	v_pk_mul_f32 v[142:143], v[142:143], s[28:29] op_sel_hi:[1,0]
	s_nop 0
	v_fma_f32 v143, -v142, v142, v143
	v_add_f32_e32 v143, 0x3727c5ac, v143
	v_rsq_f32_e32 v254, v143
	s_waitcnt vmcnt(3)
	v_sub_f32_e32 v135, v135, v142
	v_sub_f32_e32 v134, v134, v142
	v_sub_f32_e32 v133, v133, v142
	v_sub_f32_e32 v132, v132, v142
	s_waitcnt vmcnt(2)
	v_sub_f32_e32 v139, v139, v142
	v_sub_f32_e32 v138, v138, v142
	v_sub_f32_e32 v137, v137, v142
	v_sub_f32_e32 v136, v136, v142
	s_nop 0
	s_nop 1
	v_mov_b32_e32 v144, v254
	v_pk_mul_f32 v[132:133], v[132:133], v[144:145] op_sel_hi:[1,0]
	v_pk_mul_f32 v[134:135], v[134:135], v[144:145] op_sel_hi:[1,0]
	v_pk_mul_f32 v[136:137], v[136:137], v[144:145] op_sel_hi:[1,0]
	v_pk_mul_f32 v[138:139], v[138:139], v[144:145] op_sel_hi:[1,0]
	v_pk_fma_f32 v[134:135], v[30:31], v[134:135], v[18:19]
	v_pk_fma_f32 v[132:133], v[28:29], v[132:133], v[16:17]
	v_pk_fma_f32 v[138:139], v[22:23], v[138:139], v[26:27]
	v_pk_fma_f32 v[136:137], v[20:21], v[136:137], v[24:25]
	v_pk_mul_f32 v[132:133], v[132:133], s[30:31] op_sel_hi:[1,0]
	v_pk_mul_f32 v[134:135], v[134:135], s[30:31] op_sel_hi:[1,0]
	v_pk_mul_f32 v[136:137], v[136:137], s[30:31] op_sel_hi:[1,0]
	v_pk_mul_f32 v[138:139], v[138:139], s[30:31] op_sel_hi:[1,0]
	v_pk_fma_f32 v[126:127], v[126:127], s[36:37], v[134:135] op_sel_hi:[1,0,1]
	v_pk_fma_f32 v[124:125], v[124:125], s[36:37], v[132:133] op_sel_hi:[1,0,1]
	v_pk_fma_f32 v[122:123], v[122:123], s[36:37], v[138:139] op_sel_hi:[1,0,1]
	v_pk_fma_f32 v[120:121], v[120:121], s[36:37], v[136:137] op_sel_hi:[1,0,1]
	v_fmamk_f32 v132, v126, 0x41980000, v252
	v_fmamk_f32 v133, v127, 0x41980000, v252
	v_fmamk_f32 v134, v124, 0x41980000, v252
	v_fmamk_f32 v135, v125, 0x41980000, v252
	v_fmamk_f32 v136, v122, 0x41980000, v252
	v_fmamk_f32 v137, v123, 0x41980000, v252
	v_fmamk_f32 v138, v120, 0x41980000, v252
	v_fmamk_f32 v139, v121, 0x41980000, v252
	v_med3_f32 v134, v134, s32, v253
	v_med3_f32 v135, v135, s32, v253
	v_med3_f32 v132, v132, s32, v253
	v_med3_f32 v133, v133, s32, v253
	v_med3_f32 v138, v138, s32, v253
	v_med3_f32 v139, v139, s32, v253
	v_med3_f32 v136, v136, s32, v253
	v_med3_f32 v137, v137, s32, v253
	v_perm_b32 v134, v135, v134, s65
	v_perm_b32 v132, v133, v132, s66
	v_perm_b32 v133, v139, v138, s65
	v_perm_b32 v135, v137, v136, s66
	v_or_b32_e32 v132, v134, v132
	v_or_b32_e32 v133, v133, v135
	global_store_dwordx4 v[130:131], v[124:127], off nt
	global_store_dwordx4 v[130:131], v[120:123], off offset:16 nt
	global_store_dwordx2 v[140:141], v[132:133], off
	s_waitcnt vmcnt(3)
	s_nop 1
	v_mov_b32_e32 v132, v228
	v_mov_b32_e32 v133, v229
	v_mov_b32_e32 v134, v230
	v_mov_b32_e32 v135, v231
	v_mov_b32_e32 v136, v232
	v_mov_b32_e32 v137, v233
	v_mov_b32_e32 v138, v234
	v_mov_b32_e32 v139, v235
	v_add_f32_e32 v143, v124, v125
	v_add_f32_e32 v145, v126, v127
	v_add_f32_e32 v146, v120, v121
	v_add_f32_e32 v147, v122, v123
	v_mul_f32_e32 v125, v125, v125
	v_mul_f32_e32 v127, v127, v127
	v_mul_f32_e32 v121, v121, v121
	v_mul_f32_e32 v123, v123, v123
	v_add_f32_e32 v143, v143, v145
	v_add_f32_e32 v145, v146, v147
	v_fmac_f32_e32 v125, v124, v124
	v_fmac_f32_e32 v127, v126, v126
	v_fmac_f32_e32 v121, v120, v120
	v_fmac_f32_e32 v123, v122, v122
	v_add_f32_e32 v120, v143, v145
	v_add_f32_e32 v122, v125, v127
	v_add_f32_e32 v121, v121, v123
	v_add_f32_e32 v143, 0, v120
	v_add_f32_e32 v145, v122, v121
	v_sub_f32_e32 v121, v135, v142
	v_sub_f32_e32 v120, v134, v142
	v_sub_f32_e32 v123, v133, v142
	v_sub_f32_e32 v122, v132, v142
	v_sub_f32_e32 v125, v139, v142
	v_sub_f32_e32 v124, v138, v142
	v_sub_f32_e32 v127, v137, v142
	v_sub_f32_e32 v126, v136, v142
	v_pk_mul_f32 v[122:123], v[122:123], v[144:145] op_sel_hi:[1,0]
	v_pk_mul_f32 v[120:121], v[120:121], v[144:145] op_sel_hi:[1,0]
	v_pk_mul_f32 v[126:127], v[126:127], v[144:145] op_sel_hi:[1,0]
	v_pk_mul_f32 v[124:125], v[124:125], v[144:145] op_sel_hi:[1,0]
	v_pk_fma_f32 v[120:121], v[10:11], v[120:121], v[14:15]
	v_pk_fma_f32 v[122:123], v[8:9], v[122:123], v[12:13]
	v_pk_fma_f32 v[124:125], v[2:3], v[124:125], v[6:7]
	v_pk_fma_f32 v[126:127], v[0:1], v[126:127], v[4:5]
	v_pk_mul_f32 v[122:123], v[122:123], s[30:31] op_sel_hi:[1,0]
	v_pk_mul_f32 v[120:121], v[120:121], s[30:31] op_sel_hi:[1,0]
	v_pk_mul_f32 v[126:127], v[126:127], s[30:31] op_sel_hi:[1,0]
	v_pk_mul_f32 v[124:125], v[124:125], s[30:31] op_sel_hi:[1,0]
	v_pk_fma_f32 v[118:119], v[118:119], s[36:37], v[120:121] op_sel_hi:[1,0,1]
	v_pk_fma_f32 v[116:117], v[116:117], s[36:37], v[122:123] op_sel_hi:[1,0,1]
	v_pk_fma_f32 v[114:115], v[114:115], s[36:37], v[124:125] op_sel_hi:[1,0,1]
	v_pk_fma_f32 v[112:113], v[112:113], s[36:37], v[126:127] op_sel_hi:[1,0,1]
	global_store_dwordx4 v[130:131], v[116:119], off offset:512 nt
	global_store_dwordx4 v[130:131], v[112:115], off offset:528 nt
	v_add_f32_e32 v130, v116, v117
	v_add_f32_e32 v131, v118, v119
	v_add_f32_e32 v132, v112, v113
	v_add_f32_e32 v133, v114, v115
	v_mul_f32_e32 v134, v117, v117
	v_mul_f32_e32 v135, v119, v119
	v_mul_f32_e32 v136, v113, v113
	v_mul_f32_e32 v137, v115, v115
	v_fmamk_f32 v122, v116, 0x41980000, v252
	v_fmamk_f32 v123, v117, 0x41980000, v252
	v_fmamk_f32 v124, v114, 0x41980000, v252
	v_fmamk_f32 v125, v115, 0x41980000, v252
	v_fmamk_f32 v126, v112, 0x41980000, v252
	v_fmamk_f32 v127, v113, 0x41980000, v252
	v_add_f32_e32 v113, v130, v131
	v_add_f32_e32 v115, v132, v133
	v_fmac_f32_e32 v134, v116, v116
	v_fmac_f32_e32 v135, v118, v118
	v_fmac_f32_e32 v136, v112, v112
	v_fmac_f32_e32 v137, v114, v114
	v_med3_f32 v112, v122, s32, v253
	v_add_f32_e32 v113, v113, v115
	v_add_f32_e32 v115, v134, v135
	v_add_f32_e32 v122, v136, v137
	v_med3_f32 v114, v123, s32, v253
	v_add_f32_e32 v115, v115, v122
	v_add_f32_e32 v113, v113, v143
	v_add_f32_e32 v115, v145, v115
	v_perm_b32 v112, v114, v112, s65
	v_mov_b32_e32 v114, v113
	s_nop 1
	v_permlane16_swap_b32_e32 v113, v114
	v_mov_b32_e32 v122, v115
	s_nop 1
	v_permlane16_swap_b32_e32 v115, v122
	v_fmamk_f32 v120, v118, 0x41980000, v252
	v_fmamk_f32 v121, v119, 0x41980000, v252
	v_med3_f32 v118, v126, s32, v253
	v_med3_f32 v116, v120, s32, v253
	v_med3_f32 v117, v121, s32, v253
	v_perm_b32 v116, v117, v116, s66
	v_or_b32_e32 v116, v112, v116
	s_waitcnt lgkmcnt(0)
; __device__ __forceinline__ u32x2 pack8i8(const f32x4 a, const f32x4 b) { return (u32x2){pack4i8(a), pack4i8(b)}; }
; __device__ __forceinline__ unsigned pack4i8(const f32x4 t) {
;     const float M = 12582912.f; const unsigned a = __float_as_uint(__builtin_amdgcn_fmed3f(t[0], -127.f, 127.f) + M), b = __float_as_uint(__builtin_amdgcn_fmed3f(t[1], -127.f, 127.f) + M),
;     __device__ __forceinline__ void operator()(EPI_ARGS) const {
;     ...
;             for (int m = 0; m < 4; ++m) { const int row = row0 + ai * HALF + m * 16; const size_t off = (size_t)row * DM + col0;
;                 float mu = 0.f, rs = 1.f; if constexpr (RESLN) ln_stats(stin, row, mu, rs);
;                 float ss = 0.f, qq = 0.f;
; #pragma unroll
;                 for (int bj = 0; bj < 2; ++bj) { f32x4 r0 = __builtin_nontemporal_load((const f32x4*)(res + off + bj * HALF)), r1 = __builtin_nontemporal_load((const f32x4*)(res + off + bj * HALF + 4));
;                     if constexpr (RESLN) { r0 = (r0 - mu) * rs * gg[bj][0] + bb[bj][0]; r1 = (r1 - mu) * rs * gg[bj][1] + bb[bj][1]; }
;                     const f32x4 y0 = r0 * DN_ALPHA + acc[ai][bj][m][0] * ascale, y1 = r1 * DN_ALPHA + acc[ai][bj][m][1] * ascale;
;                     if constexpr (COPY != 4) { __builtin_nontemporal_store(y0, (f32x4*)(Y + off + bj * HALF)); __builtin_nontemporal_store(y1, (f32x4*)(Y + off + bj * HALF + 4)); }
;                     if constexpr (STATS) { ss += ((y0[0] + y0[1]) + (y0[2] + y0[3])) + ((y1[0] + y1[1]) + (y1[2] + y1[3]));
;                         qq += ((y0[0] * y0[0] + y0[1] * y0[1]) + (y0[2] * y0[2] + y0[3] * y0[3])) + ((y1[0] * y1[0] + y1[1] * y1[1]) + (y1[2] * y1[2] + y1[3] * y1[3])); }
;                     if constexpr (COPY == 1) *(u32x2*)((unsigned char*)copy + off + bj * HALF) = pack8fp8(y0 * cscale, y1 * cscale);
;                     if constexpr (COPY == 3) *(u32x2*)((unsigned char*)copy + off + bj * HALF) = pack8i8(y0 * cscale, y1 * cscale);
;                     if constexpr (COPY == 2 || COPY == 4) *(u32x4*)((bf16_t*)copy + off + bj * HALF) = pack8bf(y0, y1); }
;                 if constexpr (STATS) { ss += __shfl_xor(ss, 16); ss += __shfl_xor(ss, 32); qq += __shfl_xor(qq, 16); qq += __shfl_xor(qq, 32);
;                     if (fq == 0) { unsafeAtomicAdd(stout + 2 * (size_t)row, ss); unsafeAtomicAdd(stout + 2 * (size_t)row + 1, qq); } }
	v_add_f32_e32 v112, v113, v114
	s_waitcnt lgkmcnt(0)
	v_add_f32_e32 v114, v115, v122
	v_mov_b32_e32 v113, v112
	s_nop 1
	v_permlane32_swap_b32_e32 v112, v113
	v_mov_b32_e32 v115, v114
	s_nop 1
	v_permlane32_swap_b32_e32 v114, v115
	v_med3_f32 v119, v127, s32, v253
	v_med3_f32 v120, v124, s32, v253
	v_med3_f32 v121, v125, s32, v253
	v_perm_b32 v117, v119, v118, s65
	v_perm_b32 v118, v121, v120, s66
	v_or_b32_e32 v117, v117, v118
	global_store_dwordx2 v[140:141], v[116:117], off offset:128
	s_and_saveexec_b64 s[6:7], s[2:3]
	s_cbranch_execz .LBB0_3867
	v_lshl_add_u64 v[116:117], s[12:13], 0, v[128:129]
	s_waitcnt lgkmcnt(0)
	v_add_f32_e32 v112, v112, v113
	s_waitcnt lgkmcnt(0)
	v_add_f32_e32 v113, v114, v115
	global_atomic_add_f32 v[116:117], v112, off
	global_atomic_add_f32 v[116:117], v113, off offset:4
.LBB0_3867:
	s_or_b64 exec, exec, s[6:7]
	v_or_b32_e32 v112, 48, v178
	s_waitcnt lgkmcnt(1)
	v_ashrrev_i32_e32 v113, 31, v112
	s_waitcnt lgkmcnt(0)
	v_lshlrev_b64 v[114:115], 11, v[112:113]
	v_lshlrev_b64 v[112:113], 3, v[112:113]
	v_lshl_add_u64 v[124:125], v[114:115], 0, v[176:177]
	v_lshl_add_u64 v[114:115], s[14:15], 0, v[112:113]
	global_load_dwordx2 v[126:127], v[114:115], off
	v_lshl_add_u64 v[114:115], v[124:125], 2, s[18:19]
	global_load_dwordx4 v[116:119], v[114:115], off nt
	global_load_dwordx4 v[120:123], v[114:115], off offset:16 nt
	global_load_dwordx4 v[228:231], v[114:115], off offset:512 nt
	global_load_dwordx4 v[232:235], v[114:115], off offset:528 nt
	v_lshl_add_u64 v[124:125], s[20:21], 0, v[124:125]
	s_waitcnt vmcnt(4)
	v_pk_mul_f32 v[126:127], v[126:127], s[28:29] op_sel_hi:[1,0]
	s_nop 0
	v_fma_f32 v127, -v126, v126, v127
	v_add_f32_e32 v127, 0x3727c5ac, v127
	v_rsq_f32_e32 v254, v127
	s_waitcnt vmcnt(3)
	v_sub_f32_e32 v119, v119, v126
	v_sub_f32_e32 v118, v118, v126
	v_sub_f32_e32 v117, v117, v126
	v_sub_f32_e32 v116, v116, v126
	s_waitcnt vmcnt(2)
	v_sub_f32_e32 v123, v123, v126
	v_sub_f32_e32 v122, v122, v126
	v_sub_f32_e32 v121, v121, v126
	v_sub_f32_e32 v120, v120, v126
	s_nop 0
	s_nop 1
	v_mov_b32_e32 v128, v254
	v_pk_mul_f32 v[116:117], v[116:117], v[128:129] op_sel_hi:[1,0]
	v_pk_mul_f32 v[118:119], v[118:119], v[128:129] op_sel_hi:[1,0]
	v_pk_mul_f32 v[120:121], v[120:121], v[128:129] op_sel_hi:[1,0]
	v_pk_mul_f32 v[122:123], v[122:123], v[128:129] op_sel_hi:[1,0]
	v_pk_fma_f32 v[118:119], v[30:31], v[118:119], v[18:19]
	v_pk_fma_f32 v[116:117], v[28:29], v[116:117], v[16:17]
	v_pk_fma_f32 v[122:123], v[22:23], v[122:123], v[26:27]
	v_pk_fma_f32 v[120:121], v[20:21], v[120:121], v[24:25]
	v_pk_mul_f32 v[116:117], v[116:117], s[30:31] op_sel_hi:[1,0]
	v_pk_mul_f32 v[118:119], v[118:119], s[30:31] op_sel_hi:[1,0]
	v_pk_mul_f32 v[120:121], v[120:121], s[30:31] op_sel_hi:[1,0]
	v_pk_mul_f32 v[122:123], v[122:123], s[30:31] op_sel_hi:[1,0]
	v_pk_fma_f32 v[110:111], v[110:111], s[36:37], v[118:119] op_sel_hi:[1,0,1]
	v_pk_fma_f32 v[108:109], v[108:109], s[36:37], v[116:117] op_sel_hi:[1,0,1]
	v_pk_fma_f32 v[106:107], v[106:107], s[36:37], v[122:123] op_sel_hi:[1,0,1]
	v_pk_fma_f32 v[104:105], v[104:105], s[36:37], v[120:121] op_sel_hi:[1,0,1]
	v_fmamk_f32 v116, v110, 0x41980000, v252
	v_fmamk_f32 v117, v111, 0x41980000, v252
	v_fmamk_f32 v118, v108, 0x41980000, v252
	v_fmamk_f32 v119, v109, 0x41980000, v252
	v_fmamk_f32 v120, v106, 0x41980000, v252
	v_fmamk_f32 v121, v107, 0x41980000, v252
	v_fmamk_f32 v122, v104, 0x41980000, v252
	v_fmamk_f32 v123, v105, 0x41980000, v252
	v_med3_f32 v118, v118, s32, v253
	v_med3_f32 v119, v119, s32, v253
	v_med3_f32 v116, v116, s32, v253
	v_med3_f32 v117, v117, s32, v253
	v_med3_f32 v122, v122, s32, v253
	v_med3_f32 v123, v123, s32, v253
	v_med3_f32 v120, v120, s32, v253
	v_med3_f32 v121, v121, s32, v253
	v_perm_b32 v118, v119, v118, s65
	v_perm_b32 v116, v117, v116, s66
	v_perm_b32 v117, v123, v122, s65
	v_perm_b32 v119, v121, v120, s66
	v_or_b32_e32 v116, v118, v116
	v_or_b32_e32 v117, v117, v119
	global_store_dwordx4 v[114:115], v[108:111], off nt
	global_store_dwordx4 v[114:115], v[104:107], off offset:16 nt
	global_store_dwordx2 v[124:125], v[116:117], off
	s_waitcnt vmcnt(3)
	s_nop 1
	v_mov_b32_e32 v116, v228
	v_mov_b32_e32 v117, v229
	v_mov_b32_e32 v118, v230
	v_mov_b32_e32 v119, v231
	v_mov_b32_e32 v120, v232
	v_mov_b32_e32 v121, v233
	v_mov_b32_e32 v122, v234
	v_mov_b32_e32 v123, v235
	v_add_f32_e32 v127, v108, v109
	v_add_f32_e32 v129, v110, v111
	v_add_f32_e32 v130, v104, v105
	v_add_f32_e32 v131, v106, v107
	v_mul_f32_e32 v109, v109, v109
	v_mul_f32_e32 v111, v111, v111
	v_mul_f32_e32 v105, v105, v105
	v_mul_f32_e32 v107, v107, v107
	v_add_f32_e32 v127, v127, v129
	v_add_f32_e32 v129, v130, v131
	v_fmac_f32_e32 v109, v108, v108
	v_fmac_f32_e32 v111, v110, v110
	v_fmac_f32_e32 v105, v104, v104
	v_fmac_f32_e32 v107, v106, v106
	v_add_f32_e32 v104, v127, v129
	v_add_f32_e32 v106, v109, v111
	v_add_f32_e32 v105, v105, v107
	v_add_f32_e32 v127, 0, v104
	v_add_f32_e32 v129, v106, v105
	v_sub_f32_e32 v105, v119, v126
	v_sub_f32_e32 v104, v118, v126
	v_sub_f32_e32 v107, v117, v126
	v_sub_f32_e32 v106, v116, v126
	v_sub_f32_e32 v109, v123, v126
	v_sub_f32_e32 v108, v122, v126
	v_sub_f32_e32 v111, v121, v126
	v_sub_f32_e32 v110, v120, v126
	v_pk_mul_f32 v[106:107], v[106:107], v[128:129] op_sel_hi:[1,0]
	v_pk_mul_f32 v[104:105], v[104:105], v[128:129] op_sel_hi:[1,0]
	v_pk_mul_f32 v[110:111], v[110:111], v[128:129] op_sel_hi:[1,0]
	v_pk_mul_f32 v[108:109], v[108:109], v[128:129] op_sel_hi:[1,0]
	v_pk_fma_f32 v[104:105], v[10:11], v[104:105], v[14:15]
	v_pk_fma_f32 v[106:107], v[8:9], v[106:107], v[12:13]
	v_pk_fma_f32 v[108:109], v[2:3], v[108:109], v[6:7]
; __device__ __forceinline__ u32x2 pack8i8(const f32x4 a, const f32x4 b) { return (u32x2){pack4i8(a), pack4i8(b)}; }
; __device__ __forceinline__ unsigned pack4i8(const f32x4 t) {
;     const float M = 12582912.f; const unsigned a = __float_as_uint(__builtin_amdgcn_fmed3f(t[0], -127.f, 127.f) + M), b = __float_as_uint(__builtin_amdgcn_fmed3f(t[1], -127.f, 127.f) + M),
;     __device__ __forceinline__ void operator()(EPI_ARGS) const {
;     ...
;             for (int m = 0; m < 4; ++m) { const int row = row0 + ai * HALF + m * 16; const size_t off = (size_t)row * DM + col0;
;                 float mu = 0.f, rs = 1.f; if constexpr (RESLN) ln_stats(stin, row, mu, rs);
;                 float ss = 0.f, qq = 0.f;
; #pragma unroll
;                 for (int bj = 0; bj < 2; ++bj) { f32x4 r0 = __builtin_nontemporal_load((const f32x4*)(res + off + bj * HALF)), r1 = __builtin_nontemporal_load((const f32x4*)(res + off + bj * HALF + 4));
;                     if constexpr (RESLN) { r0 = (r0 - mu) * rs * gg[bj][0] + bb[bj][0]; r1 = (r1 - mu) * rs * gg[bj][1] + bb[bj][1]; }
;                     const f32x4 y0 = r0 * DN_ALPHA + acc[ai][bj][m][0] * ascale, y1 = r1 * DN_ALPHA + acc[ai][bj][m][1] * ascale;
;                     if constexpr (COPY != 4) { __builtin_nontemporal_store(y0, (f32x4*)(Y + off + bj * HALF)); __builtin_nontemporal_store(y1, (f32x4*)(Y + off + bj * HALF + 4)); }
;                     if constexpr (STATS) { ss += ((y0[0] + y0[1]) + (y0[2] + y0[3])) + ((y1[0] + y1[1]) + (y1[2] + y1[3]));
;                         qq += ((y0[0] * y0[0] + y0[1] * y0[1]) + (y0[2] * y0[2] + y0[3] * y0[3])) + ((y1[0] * y1[0] + y1[1] * y1[1]) + (y1[2] * y1[2] + y1[3] * y1[3])); }
;                     if constexpr (COPY == 1) *(u32x2*)((unsigned char*)copy + off + bj * HALF) = pack8fp8(y0 * cscale, y1 * cscale);
;                     if constexpr (COPY == 3) *(u32x2*)((unsigned char*)copy + off + bj * HALF) = pack8i8(y0 * cscale, y1 * cscale);
;                     if constexpr (COPY == 2 || COPY == 4) *(u32x4*)((bf16_t*)copy + off + bj * HALF) = pack8bf(y0, y1); }
;                 if constexpr (STATS) { ss += __shfl_xor(ss, 16); ss += __shfl_xor(ss, 32); qq += __shfl_xor(qq, 16); qq += __shfl_xor(qq, 32);
;                     if (fq == 0) { unsafeAtomicAdd(stout + 2 * (size_t)row, ss); unsafeAtomicAdd(stout + 2 * (size_t)row + 1, qq); } }
	v_pk_fma_f32 v[110:111], v[0:1], v[110:111], v[4:5]
	v_pk_mul_f32 v[106:107], v[106:107], s[30:31] op_sel_hi:[1,0]
	v_pk_mul_f32 v[104:105], v[104:105], s[30:31] op_sel_hi:[1,0]
	v_pk_mul_f32 v[110:111], v[110:111], s[30:31] op_sel_hi:[1,0]
	v_pk_mul_f32 v[108:109], v[108:109], s[30:31] op_sel_hi:[1,0]
	v_pk_fma_f32 v[102:103], v[102:103], s[36:37], v[104:105] op_sel_hi:[1,0,1]
	v_pk_fma_f32 v[100:101], v[100:101], s[36:37], v[106:107] op_sel_hi:[1,0,1]
	v_pk_fma_f32 v[98:99], v[98:99], s[36:37], v[108:109] op_sel_hi:[1,0,1]
	v_pk_fma_f32 v[96:97], v[96:97], s[36:37], v[110:111] op_sel_hi:[1,0,1]
	global_store_dwordx4 v[114:115], v[100:103], off offset:512 nt
	global_store_dwordx4 v[114:115], v[96:99], off offset:528 nt
	v_add_f32_e32 v114, v100, v101
	v_add_f32_e32 v115, v102, v103
	v_add_f32_e32 v116, v96, v97
	v_add_f32_e32 v117, v98, v99
	v_mul_f32_e32 v118, v101, v101
	v_mul_f32_e32 v119, v103, v103
	v_mul_f32_e32 v120, v97, v97
	v_mul_f32_e32 v121, v99, v99
	v_fmamk_f32 v106, v100, 0x41980000, v252
	v_fmamk_f32 v107, v101, 0x41980000, v252
	v_fmamk_f32 v108, v98, 0x41980000, v252
	v_fmamk_f32 v109, v99, 0x41980000, v252
	v_fmamk_f32 v110, v96, 0x41980000, v252
	v_fmamk_f32 v111, v97, 0x41980000, v252
	v_add_f32_e32 v97, v114, v115
	v_add_f32_e32 v99, v116, v117
	v_fmac_f32_e32 v118, v100, v100
	v_fmac_f32_e32 v119, v102, v102
	v_fmac_f32_e32 v120, v96, v96
	v_fmac_f32_e32 v121, v98, v98
	v_med3_f32 v96, v106, s32, v253
	v_add_f32_e32 v97, v97, v99
	v_add_f32_e32 v99, v118, v119
	v_add_f32_e32 v106, v120, v121
	v_med3_f32 v98, v107, s32, v253
	v_add_f32_e32 v99, v99, v106
	v_add_f32_e32 v97, v97, v127
	v_add_f32_e32 v99, v129, v99
	v_perm_b32 v96, v98, v96, s65
	v_mov_b32_e32 v98, v97
	s_nop 1
	v_permlane16_swap_b32_e32 v97, v98
	v_mov_b32_e32 v106, v99
	s_nop 1
	v_permlane16_swap_b32_e32 v99, v106
	v_fmamk_f32 v104, v102, 0x41980000, v252
	v_fmamk_f32 v105, v103, 0x41980000, v252
	v_med3_f32 v102, v110, s32, v253
	v_med3_f32 v100, v104, s32, v253
	v_med3_f32 v101, v105, s32, v253
	v_perm_b32 v100, v101, v100, s66
	v_or_b32_e32 v100, v96, v100
	s_waitcnt lgkmcnt(0)
	v_add_f32_e32 v96, v97, v98
	s_waitcnt lgkmcnt(0)
	v_add_f32_e32 v98, v99, v106
	v_mov_b32_e32 v97, v96
	s_nop 1
	v_permlane32_swap_b32_e32 v96, v97
	v_mov_b32_e32 v99, v98
	s_nop 1
	v_permlane32_swap_b32_e32 v98, v99
	v_med3_f32 v103, v111, s32, v253
	v_med3_f32 v104, v108, s32, v253
	v_med3_f32 v105, v109, s32, v253
	v_perm_b32 v101, v103, v102, s65
	v_perm_b32 v102, v105, v104, s66
	v_or_b32_e32 v101, v101, v102
	global_store_dwordx2 v[124:125], v[100:101], off offset:128
	s_and_saveexec_b64 s[6:7], s[2:3]
	s_cbranch_execz .LBB0_3869
	v_lshl_add_u64 v[100:101], s[12:13], 0, v[112:113]
	s_waitcnt lgkmcnt(0)
	v_add_f32_e32 v96, v96, v97
	s_waitcnt lgkmcnt(0)
	v_add_f32_e32 v97, v98, v99
	global_atomic_add_f32 v[100:101], v96, off
	global_atomic_add_f32 v[100:101], v97, off offset:4
.LBB0_3869:
	s_or_b64 exec, exec, s[6:7]
	v_add_u32_e32 v96, 0x80, v178
	s_waitcnt lgkmcnt(1)
	v_ashrrev_i32_e32 v97, 31, v96
	s_waitcnt lgkmcnt(0)
	v_lshlrev_b64 v[98:99], 11, v[96:97]
	v_lshlrev_b64 v[96:97], 3, v[96:97]
	v_lshl_add_u64 v[108:109], v[98:99], 0, v[176:177]
	v_lshl_add_u64 v[98:99], s[14:15], 0, v[96:97]
	global_load_dwordx2 v[110:111], v[98:99], off
	v_lshl_add_u64 v[98:99], v[108:109], 2, s[18:19]
	global_load_dwordx4 v[100:103], v[98:99], off nt
	global_load_dwordx4 v[104:107], v[98:99], off offset:16 nt
	global_load_dwordx4 v[228:231], v[98:99], off offset:512 nt
	global_load_dwordx4 v[232:235], v[98:99], off offset:528 nt
	v_lshl_add_u64 v[108:109], s[20:21], 0, v[108:109]
	s_waitcnt vmcnt(4)
	v_pk_mul_f32 v[110:111], v[110:111], s[28:29] op_sel_hi:[1,0]
	s_nop 0
	v_fma_f32 v111, -v110, v110, v111
	v_add_f32_e32 v111, 0x3727c5ac, v111
	v_rsq_f32_e32 v254, v111
	s_waitcnt vmcnt(3)
	v_sub_f32_e32 v103, v103, v110
	v_sub_f32_e32 v102, v102, v110
	v_sub_f32_e32 v101, v101, v110
	v_sub_f32_e32 v100, v100, v110
	s_waitcnt vmcnt(2)
	v_sub_f32_e32 v107, v107, v110
	v_sub_f32_e32 v106, v106, v110
	v_sub_f32_e32 v105, v105, v110
	v_sub_f32_e32 v104, v104, v110
	s_nop 0
	s_nop 1
	v_mov_b32_e32 v112, v254
	v_pk_mul_f32 v[100:101], v[100:101], v[112:113] op_sel_hi:[1,0]
	v_pk_mul_f32 v[102:103], v[102:103], v[112:113] op_sel_hi:[1,0]
	v_pk_mul_f32 v[104:105], v[104:105], v[112:113] op_sel_hi:[1,0]
	v_pk_mul_f32 v[106:107], v[106:107], v[112:113] op_sel_hi:[1,0]
	v_pk_fma_f32 v[102:103], v[30:31], v[102:103], v[18:19]
	v_pk_fma_f32 v[100:101], v[28:29], v[100:101], v[16:17]
	v_pk_fma_f32 v[106:107], v[22:23], v[106:107], v[26:27]
	v_pk_fma_f32 v[104:105], v[20:21], v[104:105], v[24:25]
	v_pk_mul_f32 v[100:101], v[100:101], s[30:31] op_sel_hi:[1,0]
	v_pk_mul_f32 v[102:103], v[102:103], s[30:31] op_sel_hi:[1,0]
	v_pk_mul_f32 v[104:105], v[104:105], s[30:31] op_sel_hi:[1,0]
	v_pk_mul_f32 v[106:107], v[106:107], s[30:31] op_sel_hi:[1,0]
	v_pk_fma_f32 v[94:95], v[94:95], s[36:37], v[102:103] op_sel_hi:[1,0,1]
	v_pk_fma_f32 v[92:93], v[92:93], s[36:37], v[100:101] op_sel_hi:[1,0,1]
	v_pk_fma_f32 v[90:91], v[90:91], s[36:37], v[106:107] op_sel_hi:[1,0,1]
	v_pk_fma_f32 v[88:89], v[88:89], s[36:37], v[104:105] op_sel_hi:[1,0,1]
	v_fmamk_f32 v100, v94, 0x41980000, v252
	v_fmamk_f32 v101, v95, 0x41980000, v252
	v_fmamk_f32 v102, v92, 0x41980000, v252
	v_fmamk_f32 v103, v93, 0x41980000, v252
	v_fmamk_f32 v104, v90, 0x41980000, v252
	v_fmamk_f32 v105, v91, 0x41980000, v252
	v_fmamk_f32 v106, v88, 0x41980000, v252
	v_fmamk_f32 v107, v89, 0x41980000, v252
	v_med3_f32 v102, v102, s32, v253
	v_med3_f32 v103, v103, s32, v253
	v_med3_f32 v100, v100, s32, v253
	v_med3_f32 v101, v101, s32, v253
	v_med3_f32 v106, v106, s32, v253
	v_med3_f32 v107, v107, s32, v253
	v_med3_f32 v104, v104, s32, v253
	v_med3_f32 v105, v105, s32, v253
	v_perm_b32 v102, v103, v102, s65
	v_perm_b32 v100, v101, v100, s66
	v_perm_b32 v101, v107, v106, s65
	v_perm_b32 v103, v105, v104, s66
	v_or_b32_e32 v100, v102, v100
	v_or_b32_e32 v101, v101, v103
	global_store_dwordx4 v[98:99], v[92:95], off nt
	global_store_dwordx4 v[98:99], v[88:91], off offset:16 nt
	global_store_dwordx2 v[108:109], v[100:101], off
	s_waitcnt vmcnt(3)
; __device__ __forceinline__ u32x2 pack8i8(const f32x4 a, const f32x4 b) { return (u32x2){pack4i8(a), pack4i8(b)}; }
; __device__ __forceinline__ unsigned pack4i8(const f32x4 t) {
;     const float M = 12582912.f; const unsigned a = __float_as_uint(__builtin_amdgcn_fmed3f(t[0], -127.f, 127.f) + M), b = __float_as_uint(__builtin_amdgcn_fmed3f(t[1], -127.f, 127.f) + M),
;     __device__ __forceinline__ void operator()(EPI_ARGS) const {
;     ...
;             for (int m = 0; m < 4; ++m) { const int row = row0 + ai * HALF + m * 16; const size_t off = (size_t)row * DM + col0;
;                 float mu = 0.f, rs = 1.f; if constexpr (RESLN) ln_stats(stin, row, mu, rs);
;                 float ss = 0.f, qq = 0.f;
; #pragma unroll
;                 for (int bj = 0; bj < 2; ++bj) { f32x4 r0 = __builtin_nontemporal_load((const f32x4*)(res + off + bj * HALF)), r1 = __builtin_nontemporal_load((const f32x4*)(res + off + bj * HALF + 4));
;                     if constexpr (RESLN) { r0 = (r0 - mu) * rs * gg[bj][0] + bb[bj][0]; r1 = (r1 - mu) * rs * gg[bj][1] + bb[bj][1]; }
;                     const f32x4 y0 = r0 * DN_ALPHA + acc[ai][bj][m][0] * ascale, y1 = r1 * DN_ALPHA + acc[ai][bj][m][1] * ascale;
;                     if constexpr (COPY != 4) { __builtin_nontemporal_store(y0, (f32x4*)(Y + off + bj * HALF)); __builtin_nontemporal_store(y1, (f32x4*)(Y + off + bj * HALF + 4)); }
;                     if constexpr (STATS) { ss += ((y0[0] + y0[1]) + (y0[2] + y0[3])) + ((y1[0] + y1[1]) + (y1[2] + y1[3]));
;                         qq += ((y0[0] * y0[0] + y0[1] * y0[1]) + (y0[2] * y0[2] + y0[3] * y0[3])) + ((y1[0] * y1[0] + y1[1] * y1[1]) + (y1[2] * y1[2] + y1[3] * y1[3])); }
;                     if constexpr (COPY == 1) *(u32x2*)((unsigned char*)copy + off + bj * HALF) = pack8fp8(y0 * cscale, y1 * cscale);
;                     if constexpr (COPY == 3) *(u32x2*)((unsigned char*)copy + off + bj * HALF) = pack8i8(y0 * cscale, y1 * cscale);
;                     if constexpr (COPY == 2 || COPY == 4) *(u32x4*)((bf16_t*)copy + off + bj * HALF) = pack8bf(y0, y1); }
;                 if constexpr (STATS) { ss += __shfl_xor(ss, 16); ss += __shfl_xor(ss, 32); qq += __shfl_xor(qq, 16); qq += __shfl_xor(qq, 32);
;                     if (fq == 0) { unsafeAtomicAdd(stout + 2 * (size_t)row, ss); unsafeAtomicAdd(stout + 2 * (size_t)row + 1, qq); } }
	s_nop 1
	v_mov_b32_e32 v100, v228
	v_mov_b32_e32 v101, v229
	v_mov_b32_e32 v102, v230
	v_mov_b32_e32 v103, v231
	v_mov_b32_e32 v104, v232
	v_mov_b32_e32 v105, v233
	v_mov_b32_e32 v106, v234
	v_mov_b32_e32 v107, v235
	v_add_f32_e32 v111, v92, v93
	v_add_f32_e32 v113, v94, v95
	v_add_f32_e32 v114, v88, v89
	v_add_f32_e32 v115, v90, v91
	v_mul_f32_e32 v93, v93, v93
	v_mul_f32_e32 v95, v95, v95
	v_mul_f32_e32 v89, v89, v89
	v_mul_f32_e32 v91, v91, v91
	v_add_f32_e32 v111, v111, v113
	v_add_f32_e32 v113, v114, v115
	v_fmac_f32_e32 v93, v92, v92
	v_fmac_f32_e32 v95, v94, v94
	v_fmac_f32_e32 v89, v88, v88
	v_fmac_f32_e32 v91, v90, v90
	v_add_f32_e32 v88, v111, v113
	v_add_f32_e32 v90, v93, v95
	v_add_f32_e32 v89, v89, v91
	v_add_f32_e32 v111, 0, v88
	v_add_f32_e32 v113, v90, v89
	v_sub_f32_e32 v89, v103, v110
	v_sub_f32_e32 v88, v102, v110
	v_sub_f32_e32 v91, v101, v110
	v_sub_f32_e32 v90, v100, v110
	v_sub_f32_e32 v93, v107, v110
	v_sub_f32_e32 v92, v106, v110
	v_sub_f32_e32 v95, v105, v110
	v_sub_f32_e32 v94, v104, v110
	v_pk_mul_f32 v[90:91], v[90:91], v[112:113] op_sel_hi:[1,0]
	v_pk_mul_f32 v[88:89], v[88:89], v[112:113] op_sel_hi:[1,0]
	v_pk_mul_f32 v[94:95], v[94:95], v[112:113] op_sel_hi:[1,0]
	v_pk_mul_f32 v[92:93], v[92:93], v[112:113] op_sel_hi:[1,0]
	v_pk_fma_f32 v[88:89], v[10:11], v[88:89], v[14:15]
	v_pk_fma_f32 v[90:91], v[8:9], v[90:91], v[12:13]
	v_pk_fma_f32 v[92:93], v[2:3], v[92:93], v[6:7]
	v_pk_fma_f32 v[94:95], v[0:1], v[94:95], v[4:5]
	v_pk_mul_f32 v[90:91], v[90:91], s[30:31] op_sel_hi:[1,0]
	v_pk_mul_f32 v[88:89], v[88:89], s[30:31] op_sel_hi:[1,0]
	v_pk_mul_f32 v[94:95], v[94:95], s[30:31] op_sel_hi:[1,0]
	v_pk_mul_f32 v[92:93], v[92:93], s[30:31] op_sel_hi:[1,0]
	v_pk_fma_f32 v[86:87], v[86:87], s[36:37], v[88:89] op_sel_hi:[1,0,1]
	v_pk_fma_f32 v[84:85], v[84:85], s[36:37], v[90:91] op_sel_hi:[1,0,1]
	v_pk_fma_f32 v[82:83], v[82:83], s[36:37], v[92:93] op_sel_hi:[1,0,1]
	v_pk_fma_f32 v[80:81], v[80:81], s[36:37], v[94:95] op_sel_hi:[1,0,1]
	global_store_dwordx4 v[98:99], v[84:87], off offset:512 nt
	global_store_dwordx4 v[98:99], v[80:83], off offset:528 nt
	v_add_f32_e32 v98, v84, v85
	v_add_f32_e32 v99, v86, v87
	v_add_f32_e32 v100, v80, v81
	v_add_f32_e32 v101, v82, v83
	v_mul_f32_e32 v102, v85, v85
	v_mul_f32_e32 v103, v87, v87
	v_mul_f32_e32 v104, v81, v81
	v_mul_f32_e32 v105, v83, v83
	v_fmamk_f32 v90, v84, 0x41980000, v252
	v_fmamk_f32 v91, v85, 0x41980000, v252
	v_fmamk_f32 v92, v82, 0x41980000, v252
	v_fmamk_f32 v93, v83, 0x41980000, v252
	v_fmamk_f32 v94, v80, 0x41980000, v252
	v_fmamk_f32 v95, v81, 0x41980000, v252
	v_add_f32_e32 v81, v98, v99
	v_add_f32_e32 v83, v100, v101
	v_fmac_f32_e32 v102, v84, v84
	v_fmac_f32_e32 v103, v86, v86
	v_fmac_f32_e32 v104, v80, v80
	v_fmac_f32_e32 v105, v82, v82
	v_med3_f32 v80, v90, s32, v253
	v_add_f32_e32 v81, v81, v83
	v_add_f32_e32 v83, v102, v103
	v_add_f32_e32 v90, v104, v105
	v_med3_f32 v82, v91, s32, v253
	v_add_f32_e32 v83, v83, v90
	v_add_f32_e32 v81, v81, v111
	v_add_f32_e32 v83, v113, v83
	v_perm_b32 v80, v82, v80, s65
	v_mov_b32_e32 v82, v81
	s_nop 1
	v_permlane16_swap_b32_e32 v81, v82
	v_mov_b32_e32 v90, v83
	s_nop 1
	v_permlane16_swap_b32_e32 v83, v90
	v_fmamk_f32 v88, v86, 0x41980000, v252
	v_fmamk_f32 v89, v87, 0x41980000, v252
	v_med3_f32 v86, v94, s32, v253
	v_med3_f32 v84, v88, s32, v253
	v_med3_f32 v85, v89, s32, v253
	v_perm_b32 v84, v85, v84, s66
	v_or_b32_e32 v84, v80, v84
	s_waitcnt lgkmcnt(0)
	v_add_f32_e32 v80, v81, v82
	s_waitcnt lgkmcnt(0)
	v_add_f32_e32 v82, v83, v90
	v_mov_b32_e32 v81, v80
	s_nop 1
	v_permlane32_swap_b32_e32 v80, v81
	v_mov_b32_e32 v83, v82
	s_nop 1
	v_permlane32_swap_b32_e32 v82, v83
	v_med3_f32 v87, v95, s32, v253
	v_med3_f32 v88, v92, s32, v253
	v_med3_f32 v89, v93, s32, v253
	v_perm_b32 v85, v87, v86, s65
	v_perm_b32 v86, v89, v88, s66
	v_or_b32_e32 v85, v85, v86
	global_store_dwordx2 v[108:109], v[84:85], off offset:128
	s_and_saveexec_b64 s[6:7], s[2:3]
	s_cbranch_execz .LBB0_3871
	v_lshl_add_u64 v[84:85], s[12:13], 0, v[96:97]
	s_waitcnt lgkmcnt(0)
	v_add_f32_e32 v80, v80, v81
	s_waitcnt lgkmcnt(0)
	v_add_f32_e32 v81, v82, v83
	global_atomic_add_f32 v[84:85], v80, off
	global_atomic_add_f32 v[84:85], v81, off offset:4
.LBB0_3871:
	s_or_b64 exec, exec, s[6:7]
	v_add_u32_e32 v80, 0x90, v178
	s_waitcnt lgkmcnt(1)
	v_ashrrev_i32_e32 v81, 31, v80
	s_waitcnt lgkmcnt(0)
	v_lshlrev_b64 v[82:83], 11, v[80:81]
	v_lshlrev_b64 v[80:81], 3, v[80:81]
	v_lshl_add_u64 v[92:93], v[82:83], 0, v[176:177]
	v_lshl_add_u64 v[82:83], s[14:15], 0, v[80:81]
	global_load_dwordx2 v[94:95], v[82:83], off
	v_lshl_add_u64 v[82:83], v[92:93], 2, s[18:19]
	global_load_dwordx4 v[84:87], v[82:83], off nt
	global_load_dwordx4 v[88:91], v[82:83], off offset:16 nt
	global_load_dwordx4 v[228:231], v[82:83], off offset:512 nt
	global_load_dwordx4 v[232:235], v[82:83], off offset:528 nt
	v_lshl_add_u64 v[92:93], s[20:21], 0, v[92:93]
	s_waitcnt vmcnt(4)
	v_pk_mul_f32 v[94:95], v[94:95], s[28:29] op_sel_hi:[1,0]
	s_nop 0
	v_fma_f32 v95, -v94, v94, v95
	v_add_f32_e32 v95, 0x3727c5ac, v95
	v_rsq_f32_e32 v254, v95
	s_waitcnt vmcnt(3)
	v_sub_f32_e32 v87, v87, v94
	v_sub_f32_e32 v86, v86, v94
	v_sub_f32_e32 v85, v85, v94
	v_sub_f32_e32 v84, v84, v94
	s_waitcnt vmcnt(2)
; __device__ __forceinline__ u32x2 pack8i8(const f32x4 a, const f32x4 b) { return (u32x2){pack4i8(a), pack4i8(b)}; }
; __device__ __forceinline__ unsigned pack4i8(const f32x4 t) {
;     const float M = 12582912.f; const unsigned a = __float_as_uint(__builtin_amdgcn_fmed3f(t[0], -127.f, 127.f) + M), b = __float_as_uint(__builtin_amdgcn_fmed3f(t[1], -127.f, 127.f) + M),
;     __device__ __forceinline__ void operator()(EPI_ARGS) const {
;     ...
;             for (int m = 0; m < 4; ++m) { const int row = row0 + ai * HALF + m * 16; const size_t off = (size_t)row * DM + col0;
;                 float mu = 0.f, rs = 1.f; if constexpr (RESLN) ln_stats(stin, row, mu, rs);
;                 float ss = 0.f, qq = 0.f;
; #pragma unroll
;                 for (int bj = 0; bj < 2; ++bj) { f32x4 r0 = __builtin_nontemporal_load((const f32x4*)(res + off + bj * HALF)), r1 = __builtin_nontemporal_load((const f32x4*)(res + off + bj * HALF + 4));
;                     if constexpr (RESLN) { r0 = (r0 - mu) * rs * gg[bj][0] + bb[bj][0]; r1 = (r1 - mu) * rs * gg[bj][1] + bb[bj][1]; }
;                     const f32x4 y0 = r0 * DN_ALPHA + acc[ai][bj][m][0] * ascale, y1 = r1 * DN_ALPHA + acc[ai][bj][m][1] * ascale;
;                     if constexpr (COPY != 4) { __builtin_nontemporal_store(y0, (f32x4*)(Y + off + bj * HALF)); __builtin_nontemporal_store(y1, (f32x4*)(Y + off + bj * HALF + 4)); }
;                     if constexpr (STATS) { ss += ((y0[0] + y0[1]) + (y0[2] + y0[3])) + ((y1[0] + y1[1]) + (y1[2] + y1[3]));
;                         qq += ((y0[0] * y0[0] + y0[1] * y0[1]) + (y0[2] * y0[2] + y0[3] * y0[3])) + ((y1[0] * y1[0] + y1[1] * y1[1]) + (y1[2] * y1[2] + y1[3] * y1[3])); }
;                     if constexpr (COPY == 1) *(u32x2*)((unsigned char*)copy + off + bj * HALF) = pack8fp8(y0 * cscale, y1 * cscale);
;                     if constexpr (COPY == 3) *(u32x2*)((unsigned char*)copy + off + bj * HALF) = pack8i8(y0 * cscale, y1 * cscale);
;                     if constexpr (COPY == 2 || COPY == 4) *(u32x4*)((bf16_t*)copy + off + bj * HALF) = pack8bf(y0, y1); }
;                 if constexpr (STATS) { ss += __shfl_xor(ss, 16); ss += __shfl_xor(ss, 32); qq += __shfl_xor(qq, 16); qq += __shfl_xor(qq, 32);
;                     if (fq == 0) { unsafeAtomicAdd(stout + 2 * (size_t)row, ss); unsafeAtomicAdd(stout + 2 * (size_t)row + 1, qq); } }
	v_sub_f32_e32 v91, v91, v94
	v_sub_f32_e32 v90, v90, v94
	v_sub_f32_e32 v89, v89, v94
	v_sub_f32_e32 v88, v88, v94
	s_nop 0
	s_nop 1
	v_mov_b32_e32 v96, v254
	v_pk_mul_f32 v[84:85], v[84:85], v[96:97] op_sel_hi:[1,0]
	v_pk_mul_f32 v[86:87], v[86:87], v[96:97] op_sel_hi:[1,0]
	v_pk_mul_f32 v[88:89], v[88:89], v[96:97] op_sel_hi:[1,0]
	v_pk_mul_f32 v[90:91], v[90:91], v[96:97] op_sel_hi:[1,0]
	v_pk_fma_f32 v[86:87], v[30:31], v[86:87], v[18:19]
	v_pk_fma_f32 v[84:85], v[28:29], v[84:85], v[16:17]
	v_pk_fma_f32 v[90:91], v[22:23], v[90:91], v[26:27]
	v_pk_fma_f32 v[88:89], v[20:21], v[88:89], v[24:25]
	v_pk_mul_f32 v[84:85], v[84:85], s[30:31] op_sel_hi:[1,0]
	v_pk_mul_f32 v[86:87], v[86:87], s[30:31] op_sel_hi:[1,0]
	v_pk_mul_f32 v[88:89], v[88:89], s[30:31] op_sel_hi:[1,0]
	v_pk_mul_f32 v[90:91], v[90:91], s[30:31] op_sel_hi:[1,0]
	v_pk_fma_f32 v[78:79], v[78:79], s[36:37], v[86:87] op_sel_hi:[1,0,1]
	v_pk_fma_f32 v[76:77], v[76:77], s[36:37], v[84:85] op_sel_hi:[1,0,1]
	v_pk_fma_f32 v[74:75], v[74:75], s[36:37], v[90:91] op_sel_hi:[1,0,1]
	v_pk_fma_f32 v[72:73], v[72:73], s[36:37], v[88:89] op_sel_hi:[1,0,1]
	v_fmamk_f32 v84, v78, 0x41980000, v252
	v_fmamk_f32 v85, v79, 0x41980000, v252
	v_fmamk_f32 v86, v76, 0x41980000, v252
	v_fmamk_f32 v87, v77, 0x41980000, v252
	v_fmamk_f32 v88, v74, 0x41980000, v252
	v_fmamk_f32 v89, v75, 0x41980000, v252
	v_fmamk_f32 v90, v72, 0x41980000, v252
	v_fmamk_f32 v91, v73, 0x41980000, v252
	v_med3_f32 v86, v86, s32, v253
	v_med3_f32 v87, v87, s32, v253
	v_med3_f32 v84, v84, s32, v253
	v_med3_f32 v85, v85, s32, v253
	v_med3_f32 v90, v90, s32, v253
	v_med3_f32 v91, v91, s32, v253
	v_med3_f32 v88, v88, s32, v253
	v_med3_f32 v89, v89, s32, v253
	v_perm_b32 v86, v87, v86, s65
	v_perm_b32 v84, v85, v84, s66
	v_perm_b32 v85, v91, v90, s65
	v_perm_b32 v87, v89, v88, s66
	v_or_b32_e32 v84, v86, v84
	v_or_b32_e32 v85, v85, v87
	global_store_dwordx4 v[82:83], v[76:79], off nt
	global_store_dwordx4 v[82:83], v[72:75], off offset:16 nt
	global_store_dwordx2 v[92:93], v[84:85], off
	s_waitcnt vmcnt(3)
	s_nop 1
	v_mov_b32_e32 v84, v228
	v_mov_b32_e32 v85, v229
	v_mov_b32_e32 v86, v230
	v_mov_b32_e32 v87, v231
	v_mov_b32_e32 v88, v232
	v_mov_b32_e32 v89, v233
	v_mov_b32_e32 v90, v234
	v_mov_b32_e32 v91, v235
	v_add_f32_e32 v95, v76, v77
	v_add_f32_e32 v97, v78, v79
	v_add_f32_e32 v98, v72, v73
	v_add_f32_e32 v99, v74, v75
	v_mul_f32_e32 v77, v77, v77
	v_mul_f32_e32 v79, v79, v79
	v_mul_f32_e32 v73, v73, v73
	v_mul_f32_e32 v75, v75, v75
	v_add_f32_e32 v95, v95, v97
	v_add_f32_e32 v97, v98, v99
	v_fmac_f32_e32 v77, v76, v76
	v_fmac_f32_e32 v79, v78, v78
	v_fmac_f32_e32 v73, v72, v72
	v_fmac_f32_e32 v75, v74, v74
	v_add_f32_e32 v72, v95, v97
	v_add_f32_e32 v74, v77, v79
	v_add_f32_e32 v73, v73, v75
	v_add_f32_e32 v95, 0, v72
	v_add_f32_e32 v97, v74, v73
	v_sub_f32_e32 v73, v87, v94
	v_sub_f32_e32 v72, v86, v94
	v_sub_f32_e32 v75, v85, v94
	v_sub_f32_e32 v74, v84, v94
	v_sub_f32_e32 v77, v91, v94
	v_sub_f32_e32 v76, v90, v94
	v_sub_f32_e32 v79, v89, v94
	v_sub_f32_e32 v78, v88, v94
	v_pk_mul_f32 v[74:75], v[74:75], v[96:97] op_sel_hi:[1,0]
	v_pk_mul_f32 v[72:73], v[72:73], v[96:97] op_sel_hi:[1,0]
	v_pk_mul_f32 v[78:79], v[78:79], v[96:97] op_sel_hi:[1,0]
	v_pk_mul_f32 v[76:77], v[76:77], v[96:97] op_sel_hi:[1,0]
	v_pk_fma_f32 v[72:73], v[10:11], v[72:73], v[14:15]
	v_pk_fma_f32 v[74:75], v[8:9], v[74:75], v[12:13]
	v_pk_fma_f32 v[76:77], v[2:3], v[76:77], v[6:7]
	v_pk_fma_f32 v[78:79], v[0:1], v[78:79], v[4:5]
	v_pk_mul_f32 v[74:75], v[74:75], s[30:31] op_sel_hi:[1,0]
	v_pk_mul_f32 v[72:73], v[72:73], s[30:31] op_sel_hi:[1,0]
	v_pk_mul_f32 v[78:79], v[78:79], s[30:31] op_sel_hi:[1,0]
	v_pk_mul_f32 v[76:77], v[76:77], s[30:31] op_sel_hi:[1,0]
	v_pk_fma_f32 v[70:71], v[70:71], s[36:37], v[72:73] op_sel_hi:[1,0,1]
	v_pk_fma_f32 v[68:69], v[68:69], s[36:37], v[74:75] op_sel_hi:[1,0,1]
	v_pk_fma_f32 v[66:67], v[66:67], s[36:37], v[76:77] op_sel_hi:[1,0,1]
	v_pk_fma_f32 v[64:65], v[64:65], s[36:37], v[78:79] op_sel_hi:[1,0,1]
	global_store_dwordx4 v[82:83], v[68:71], off offset:512 nt
	global_store_dwordx4 v[82:83], v[64:67], off offset:528 nt
	v_add_f32_e32 v82, v68, v69
	v_add_f32_e32 v83, v70, v71
	v_add_f32_e32 v84, v64, v65
	v_add_f32_e32 v85, v66, v67
	v_mul_f32_e32 v86, v69, v69
	v_mul_f32_e32 v87, v71, v71
	v_mul_f32_e32 v88, v65, v65
	v_mul_f32_e32 v89, v67, v67
	v_fmamk_f32 v74, v68, 0x41980000, v252
	v_fmamk_f32 v75, v69, 0x41980000, v252
	v_fmamk_f32 v76, v66, 0x41980000, v252
	v_fmamk_f32 v77, v67, 0x41980000, v252
	v_fmamk_f32 v78, v64, 0x41980000, v252
	v_fmamk_f32 v79, v65, 0x41980000, v252
	v_add_f32_e32 v65, v82, v83
	v_add_f32_e32 v67, v84, v85
	v_fmac_f32_e32 v86, v68, v68
	v_fmac_f32_e32 v87, v70, v70
	v_fmac_f32_e32 v88, v64, v64
	v_fmac_f32_e32 v89, v66, v66
	v_med3_f32 v64, v74, s32, v253
	v_add_f32_e32 v65, v65, v67
	v_add_f32_e32 v67, v86, v87
	v_add_f32_e32 v74, v88, v89
	v_med3_f32 v66, v75, s32, v253
	v_add_f32_e32 v67, v67, v74
	v_add_f32_e32 v65, v65, v95
	v_add_f32_e32 v67, v97, v67
	v_perm_b32 v64, v66, v64, s65
	v_mov_b32_e32 v66, v65
	s_nop 1
	v_permlane16_swap_b32_e32 v65, v66
	v_mov_b32_e32 v74, v67
	s_nop 1
	v_permlane16_swap_b32_e32 v67, v74
	v_fmamk_f32 v72, v70, 0x41980000, v252
	v_fmamk_f32 v73, v71, 0x41980000, v252
	v_med3_f32 v70, v78, s32, v253
	v_med3_f32 v68, v72, s32, v253
	v_med3_f32 v69, v73, s32, v253
	v_perm_b32 v68, v69, v68, s66
	v_or_b32_e32 v68, v64, v68
	s_waitcnt lgkmcnt(0)
	v_add_f32_e32 v64, v65, v66
	s_waitcnt lgkmcnt(0)
	v_add_f32_e32 v66, v67, v74
	v_mov_b32_e32 v65, v64
	s_nop 1
	v_permlane32_swap_b32_e32 v64, v65
	v_mov_b32_e32 v67, v66
	s_nop 1
	v_permlane32_swap_b32_e32 v66, v67
	v_med3_f32 v71, v79, s32, v253
	v_med3_f32 v72, v76, s32, v253
	v_med3_f32 v73, v77, s32, v253
	v_perm_b32 v69, v71, v70, s65
	v_perm_b32 v70, v73, v72, s66
	v_or_b32_e32 v69, v69, v70
	global_store_dwordx2 v[92:93], v[68:69], off offset:128
	s_and_saveexec_b64 s[6:7], s[2:3]
	s_cbranch_execz .LBB0_3873
	v_lshl_add_u64 v[68:69], s[12:13], 0, v[80:81]
	s_waitcnt lgkmcnt(0)
	v_add_f32_e32 v64, v64, v65
	s_waitcnt lgkmcnt(0)
	v_add_f32_e32 v65, v66, v67
	global_atomic_add_f32 v[68:69], v64, off
	global_atomic_add_f32 v[68:69], v65, off offset:4
; __device__ __forceinline__ u32x2 pack8i8(const f32x4 a, const f32x4 b) { return (u32x2){pack4i8(a), pack4i8(b)}; }
; __device__ __forceinline__ unsigned pack4i8(const f32x4 t) {
;     const float M = 12582912.f; const unsigned a = __float_as_uint(__builtin_amdgcn_fmed3f(t[0], -127.f, 127.f) + M), b = __float_as_uint(__builtin_amdgcn_fmed3f(t[1], -127.f, 127.f) + M),
;     __device__ __forceinline__ void operator()(EPI_ARGS) const {
;     ...
;             for (int m = 0; m < 4; ++m) { const int row = row0 + ai * HALF + m * 16; const size_t off = (size_t)row * DM + col0;
;                 float mu = 0.f, rs = 1.f; if constexpr (RESLN) ln_stats(stin, row, mu, rs);
;                 float ss = 0.f, qq = 0.f;
; #pragma unroll
;                 for (int bj = 0; bj < 2; ++bj) { f32x4 r0 = __builtin_nontemporal_load((const f32x4*)(res + off + bj * HALF)), r1 = __builtin_nontemporal_load((const f32x4*)(res + off + bj * HALF + 4));
;                     if constexpr (RESLN) { r0 = (r0 - mu) * rs * gg[bj][0] + bb[bj][0]; r1 = (r1 - mu) * rs * gg[bj][1] + bb[bj][1]; }
;                     const f32x4 y0 = r0 * DN_ALPHA + acc[ai][bj][m][0] * ascale, y1 = r1 * DN_ALPHA + acc[ai][bj][m][1] * ascale;
;                     if constexpr (COPY != 4) { __builtin_nontemporal_store(y0, (f32x4*)(Y + off + bj * HALF)); __builtin_nontemporal_store(y1, (f32x4*)(Y + off + bj * HALF + 4)); }
;                     if constexpr (STATS) { ss += ((y0[0] + y0[1]) + (y0[2] + y0[3])) + ((y1[0] + y1[1]) + (y1[2] + y1[3]));
;                         qq += ((y0[0] * y0[0] + y0[1] * y0[1]) + (y0[2] * y0[2] + y0[3] * y0[3])) + ((y1[0] * y1[0] + y1[1] * y1[1]) + (y1[2] * y1[2] + y1[3] * y1[3])); }
;                     if constexpr (COPY == 1) *(u32x2*)((unsigned char*)copy + off + bj * HALF) = pack8fp8(y0 * cscale, y1 * cscale);
;                     if constexpr (COPY == 3) *(u32x2*)((unsigned char*)copy + off + bj * HALF) = pack8i8(y0 * cscale, y1 * cscale);
;                     if constexpr (COPY == 2 || COPY == 4) *(u32x4*)((bf16_t*)copy + off + bj * HALF) = pack8bf(y0, y1); }
;                 if constexpr (STATS) { ss += __shfl_xor(ss, 16); ss += __shfl_xor(ss, 32); qq += __shfl_xor(qq, 16); qq += __shfl_xor(qq, 32);
;                     if (fq == 0) { unsafeAtomicAdd(stout + 2 * (size_t)row, ss); unsafeAtomicAdd(stout + 2 * (size_t)row + 1, qq); } }
.LBB0_3873:
	s_or_b64 exec, exec, s[6:7]
	v_add_u32_e32 v64, 0xa0, v178
	s_waitcnt lgkmcnt(1)
	v_ashrrev_i32_e32 v65, 31, v64
	s_waitcnt lgkmcnt(0)
	v_lshlrev_b64 v[66:67], 11, v[64:65]
	v_lshlrev_b64 v[64:65], 3, v[64:65]
	v_lshl_add_u64 v[76:77], v[66:67], 0, v[176:177]
	v_lshl_add_u64 v[66:67], s[14:15], 0, v[64:65]
	global_load_dwordx2 v[78:79], v[66:67], off
	v_lshl_add_u64 v[66:67], v[76:77], 2, s[18:19]
	global_load_dwordx4 v[68:71], v[66:67], off nt
	global_load_dwordx4 v[72:75], v[66:67], off offset:16 nt
	global_load_dwordx4 v[228:231], v[66:67], off offset:512 nt
	global_load_dwordx4 v[232:235], v[66:67], off offset:528 nt
	v_lshl_add_u64 v[76:77], s[20:21], 0, v[76:77]
	s_waitcnt vmcnt(4)
	v_pk_mul_f32 v[78:79], v[78:79], s[28:29] op_sel_hi:[1,0]
	s_nop 0
	v_fma_f32 v79, -v78, v78, v79
	v_add_f32_e32 v79, 0x3727c5ac, v79
	v_rsq_f32_e32 v254, v79
	s_waitcnt vmcnt(3)
	v_sub_f32_e32 v71, v71, v78
	v_sub_f32_e32 v70, v70, v78
	v_sub_f32_e32 v69, v69, v78
	v_sub_f32_e32 v68, v68, v78
	s_waitcnt vmcnt(2)
	v_sub_f32_e32 v75, v75, v78
	v_sub_f32_e32 v74, v74, v78
	v_sub_f32_e32 v73, v73, v78
	v_sub_f32_e32 v72, v72, v78
	s_nop 0
	s_nop 1
	v_mov_b32_e32 v80, v254
	v_pk_mul_f32 v[68:69], v[68:69], v[80:81] op_sel_hi:[1,0]
	v_pk_mul_f32 v[70:71], v[70:71], v[80:81] op_sel_hi:[1,0]
	v_pk_mul_f32 v[72:73], v[72:73], v[80:81] op_sel_hi:[1,0]
	v_pk_mul_f32 v[74:75], v[74:75], v[80:81] op_sel_hi:[1,0]
	v_pk_fma_f32 v[70:71], v[30:31], v[70:71], v[18:19]
	v_pk_fma_f32 v[68:69], v[28:29], v[68:69], v[16:17]
	v_pk_fma_f32 v[74:75], v[22:23], v[74:75], v[26:27]
	v_pk_fma_f32 v[72:73], v[20:21], v[72:73], v[24:25]
	v_pk_mul_f32 v[68:69], v[68:69], s[30:31] op_sel_hi:[1,0]
	v_pk_mul_f32 v[70:71], v[70:71], s[30:31] op_sel_hi:[1,0]
	v_pk_mul_f32 v[72:73], v[72:73], s[30:31] op_sel_hi:[1,0]
	v_pk_mul_f32 v[74:75], v[74:75], s[30:31] op_sel_hi:[1,0]
	v_pk_fma_f32 v[62:63], v[62:63], s[36:37], v[70:71] op_sel_hi:[1,0,1]
	v_pk_fma_f32 v[60:61], v[60:61], s[36:37], v[68:69] op_sel_hi:[1,0,1]
	v_pk_fma_f32 v[58:59], v[58:59], s[36:37], v[74:75] op_sel_hi:[1,0,1]
	v_pk_fma_f32 v[56:57], v[56:57], s[36:37], v[72:73] op_sel_hi:[1,0,1]
	v_fmamk_f32 v68, v62, 0x41980000, v252
	v_fmamk_f32 v69, v63, 0x41980000, v252
	v_fmamk_f32 v70, v60, 0x41980000, v252
	v_fmamk_f32 v71, v61, 0x41980000, v252
	v_fmamk_f32 v72, v58, 0x41980000, v252
	v_fmamk_f32 v73, v59, 0x41980000, v252
	v_fmamk_f32 v74, v56, 0x41980000, v252
	v_fmamk_f32 v75, v57, 0x41980000, v252
	v_med3_f32 v70, v70, s32, v253
	v_med3_f32 v71, v71, s32, v253
	v_med3_f32 v68, v68, s32, v253
	v_med3_f32 v69, v69, s32, v253
	v_med3_f32 v74, v74, s32, v253
	v_med3_f32 v75, v75, s32, v253
	v_med3_f32 v72, v72, s32, v253
	v_med3_f32 v73, v73, s32, v253
	v_perm_b32 v70, v71, v70, s65
	v_perm_b32 v68, v69, v68, s66
	v_perm_b32 v69, v75, v74, s65
	v_perm_b32 v71, v73, v72, s66
	v_or_b32_e32 v68, v70, v68
	v_or_b32_e32 v69, v69, v71
	global_store_dwordx4 v[66:67], v[60:63], off nt
	global_store_dwordx4 v[66:67], v[56:59], off offset:16 nt
	global_store_dwordx2 v[76:77], v[68:69], off
	s_waitcnt vmcnt(3)
	s_nop 1
	v_mov_b32_e32 v68, v228
	v_mov_b32_e32 v69, v229
	v_mov_b32_e32 v70, v230
	v_mov_b32_e32 v71, v231
	v_mov_b32_e32 v72, v232
	v_mov_b32_e32 v73, v233
	v_mov_b32_e32 v74, v234
	v_mov_b32_e32 v75, v235
	v_add_f32_e32 v79, v60, v61
	v_add_f32_e32 v81, v62, v63
	v_add_f32_e32 v82, v56, v57
	v_add_f32_e32 v83, v58, v59
	v_mul_f32_e32 v61, v61, v61
	v_mul_f32_e32 v63, v63, v63
	v_mul_f32_e32 v57, v57, v57
	v_mul_f32_e32 v59, v59, v59
	v_add_f32_e32 v79, v79, v81
	v_add_f32_e32 v81, v82, v83
	v_fmac_f32_e32 v61, v60, v60
	v_fmac_f32_e32 v63, v62, v62
	v_fmac_f32_e32 v57, v56, v56
	v_fmac_f32_e32 v59, v58, v58
	v_add_f32_e32 v56, v79, v81
	v_add_f32_e32 v58, v61, v63
	v_add_f32_e32 v57, v57, v59
	v_add_f32_e32 v79, 0, v56
	v_add_f32_e32 v81, v58, v57
	v_sub_f32_e32 v57, v71, v78
	v_sub_f32_e32 v56, v70, v78
	v_sub_f32_e32 v59, v69, v78
	v_sub_f32_e32 v58, v68, v78
	v_sub_f32_e32 v61, v75, v78
	v_sub_f32_e32 v60, v74, v78
	v_sub_f32_e32 v63, v73, v78
	v_sub_f32_e32 v62, v72, v78
	v_pk_mul_f32 v[58:59], v[58:59], v[80:81] op_sel_hi:[1,0]
	v_pk_mul_f32 v[56:57], v[56:57], v[80:81] op_sel_hi:[1,0]
	v_pk_mul_f32 v[62:63], v[62:63], v[80:81] op_sel_hi:[1,0]
	v_pk_mul_f32 v[60:61], v[60:61], v[80:81] op_sel_hi:[1,0]
	v_pk_fma_f32 v[56:57], v[10:11], v[56:57], v[14:15]
	v_pk_fma_f32 v[58:59], v[8:9], v[58:59], v[12:13]
	v_pk_fma_f32 v[60:61], v[2:3], v[60:61], v[6:7]
	v_pk_fma_f32 v[62:63], v[0:1], v[62:63], v[4:5]
	v_pk_mul_f32 v[58:59], v[58:59], s[30:31] op_sel_hi:[1,0]
	v_pk_mul_f32 v[56:57], v[56:57], s[30:31] op_sel_hi:[1,0]
	v_pk_mul_f32 v[62:63], v[62:63], s[30:31] op_sel_hi:[1,0]
	v_pk_mul_f32 v[60:61], v[60:61], s[30:31] op_sel_hi:[1,0]
	v_pk_fma_f32 v[54:55], v[54:55], s[36:37], v[56:57] op_sel_hi:[1,0,1]
	v_pk_fma_f32 v[52:53], v[52:53], s[36:37], v[58:59] op_sel_hi:[1,0,1]
	v_pk_fma_f32 v[50:51], v[50:51], s[36:37], v[60:61] op_sel_hi:[1,0,1]
	v_pk_fma_f32 v[48:49], v[48:49], s[36:37], v[62:63] op_sel_hi:[1,0,1]
	global_store_dwordx4 v[66:67], v[52:55], off offset:512 nt
	global_store_dwordx4 v[66:67], v[48:51], off offset:528 nt
	v_add_f32_e32 v66, v52, v53
	v_add_f32_e32 v67, v54, v55
	v_add_f32_e32 v68, v48, v49
	v_add_f32_e32 v69, v50, v51
	v_mul_f32_e32 v70, v53, v53
	v_mul_f32_e32 v71, v55, v55
	v_mul_f32_e32 v72, v49, v49
	v_mul_f32_e32 v73, v51, v51
	v_fmamk_f32 v58, v52, 0x41980000, v252
	v_fmamk_f32 v59, v53, 0x41980000, v252
	v_fmamk_f32 v60, v50, 0x41980000, v252
	v_fmamk_f32 v61, v51, 0x41980000, v252
	v_fmamk_f32 v62, v48, 0x41980000, v252
	v_fmamk_f32 v63, v49, 0x41980000, v252
	v_add_f32_e32 v49, v66, v67
	v_add_f32_e32 v51, v68, v69
	v_fmac_f32_e32 v70, v52, v52
	v_fmac_f32_e32 v71, v54, v54
	v_fmac_f32_e32 v72, v48, v48
	v_fmac_f32_e32 v73, v50, v50
	v_med3_f32 v48, v58, s32, v253
	v_add_f32_e32 v49, v49, v51
	v_add_f32_e32 v51, v70, v71
	v_add_f32_e32 v58, v72, v73
	v_med3_f32 v50, v59, s32, v253
	v_add_f32_e32 v51, v51, v58
	v_add_f32_e32 v49, v49, v79
	v_add_f32_e32 v51, v81, v51
	v_perm_b32 v48, v50, v48, s65
	v_mov_b32_e32 v50, v49
	s_nop 1
	v_permlane16_swap_b32_e32 v49, v50
	v_mov_b32_e32 v58, v51
	s_nop 1
	v_permlane16_swap_b32_e32 v51, v58
	v_fmamk_f32 v56, v54, 0x41980000, v252
	v_fmamk_f32 v57, v55, 0x41980000, v252
	v_med3_f32 v54, v62, s32, v253
	v_med3_f32 v52, v56, s32, v253
	v_med3_f32 v53, v57, s32, v253
	v_perm_b32 v52, v53, v52, s66
	v_or_b32_e32 v52, v48, v52
	s_waitcnt lgkmcnt(0)
	v_add_f32_e32 v48, v49, v50
	s_waitcnt lgkmcnt(0)
	v_add_f32_e32 v50, v51, v58
	v_mov_b32_e32 v49, v48
	s_nop 1
	v_permlane32_swap_b32_e32 v48, v49
	v_mov_b32_e32 v51, v50
	s_nop 1
	v_permlane32_swap_b32_e32 v50, v51
	v_med3_f32 v55, v63, s32, v253
	v_med3_f32 v56, v60, s32, v253
	v_med3_f32 v57, v61, s32, v253
	v_perm_b32 v53, v55, v54, s65
	v_perm_b32 v54, v57, v56, s66
	v_or_b32_e32 v53, v53, v54
	global_store_dwordx2 v[76:77], v[52:53], off offset:128
	s_and_saveexec_b64 s[6:7], s[2:3]
	s_cbranch_execz .LBB0_3875
; __device__ __forceinline__ u32x2 pack8i8(const f32x4 a, const f32x4 b) { return (u32x2){pack4i8(a), pack4i8(b)}; }
; __device__ __forceinline__ unsigned pack4i8(const f32x4 t) {
;     const float M = 12582912.f; const unsigned a = __float_as_uint(__builtin_amdgcn_fmed3f(t[0], -127.f, 127.f) + M), b = __float_as_uint(__builtin_amdgcn_fmed3f(t[1], -127.f, 127.f) + M),
;     __device__ __forceinline__ void operator()(EPI_ARGS) const {
;     ...
;             for (int m = 0; m < 4; ++m) { const int row = row0 + ai * HALF + m * 16; const size_t off = (size_t)row * DM + col0;
;                 float mu = 0.f, rs = 1.f; if constexpr (RESLN) ln_stats(stin, row, mu, rs);
;                 float ss = 0.f, qq = 0.f;
; #pragma unroll
;                 for (int bj = 0; bj < 2; ++bj) { f32x4 r0 = __builtin_nontemporal_load((const f32x4*)(res + off + bj * HALF)), r1 = __builtin_nontemporal_load((const f32x4*)(res + off + bj * HALF + 4));
;                     if constexpr (RESLN) { r0 = (r0 - mu) * rs * gg[bj][0] + bb[bj][0]; r1 = (r1 - mu) * rs * gg[bj][1] + bb[bj][1]; }
;                     const f32x4 y0 = r0 * DN_ALPHA + acc[ai][bj][m][0] * ascale, y1 = r1 * DN_ALPHA + acc[ai][bj][m][1] * ascale;
;                     if constexpr (COPY != 4) { __builtin_nontemporal_store(y0, (f32x4*)(Y + off + bj * HALF)); __builtin_nontemporal_store(y1, (f32x4*)(Y + off + bj * HALF + 4)); }
;                     if constexpr (STATS) { ss += ((y0[0] + y0[1]) + (y0[2] + y0[3])) + ((y1[0] + y1[1]) + (y1[2] + y1[3]));
;                         qq += ((y0[0] * y0[0] + y0[1] * y0[1]) + (y0[2] * y0[2] + y0[3] * y0[3])) + ((y1[0] * y1[0] + y1[1] * y1[1]) + (y1[2] * y1[2] + y1[3] * y1[3])); }
;                     if constexpr (COPY == 1) *(u32x2*)((unsigned char*)copy + off + bj * HALF) = pack8fp8(y0 * cscale, y1 * cscale);
;                     if constexpr (COPY == 3) *(u32x2*)((unsigned char*)copy + off + bj * HALF) = pack8i8(y0 * cscale, y1 * cscale);
;                     if constexpr (COPY == 2 || COPY == 4) *(u32x4*)((bf16_t*)copy + off + bj * HALF) = pack8bf(y0, y1); }
;                 if constexpr (STATS) { ss += __shfl_xor(ss, 16); ss += __shfl_xor(ss, 32); qq += __shfl_xor(qq, 16); qq += __shfl_xor(qq, 32);
;                     if (fq == 0) { unsafeAtomicAdd(stout + 2 * (size_t)row, ss); unsafeAtomicAdd(stout + 2 * (size_t)row + 1, qq); } }
	v_lshl_add_u64 v[52:53], s[12:13], 0, v[64:65]
	s_waitcnt lgkmcnt(0)
	v_add_f32_e32 v48, v48, v49
	s_waitcnt lgkmcnt(0)
	v_add_f32_e32 v49, v50, v51
	global_atomic_add_f32 v[52:53], v48, off
	global_atomic_add_f32 v[52:53], v49, off offset:4
.LBB0_3875:
	s_or_b64 exec, exec, s[6:7]
	v_add_u32_e32 v48, 0xb0, v178
	s_waitcnt lgkmcnt(1)
	v_ashrrev_i32_e32 v49, 31, v48
	s_waitcnt lgkmcnt(0)
	v_lshlrev_b64 v[50:51], 11, v[48:49]
	v_lshlrev_b64 v[48:49], 3, v[48:49]
	v_lshl_add_u64 v[60:61], v[50:51], 0, v[176:177]
	v_lshl_add_u64 v[50:51], s[14:15], 0, v[48:49]
	global_load_dwordx2 v[62:63], v[50:51], off
	v_lshl_add_u64 v[50:51], v[60:61], 2, s[18:19]
	global_load_dwordx4 v[52:55], v[50:51], off nt
	global_load_dwordx4 v[56:59], v[50:51], off offset:16 nt
	global_load_dwordx4 v[228:231], v[50:51], off offset:512 nt
	global_load_dwordx4 v[232:235], v[50:51], off offset:528 nt
	v_lshl_add_u64 v[60:61], s[20:21], 0, v[60:61]
	s_waitcnt vmcnt(4)
	v_pk_mul_f32 v[62:63], v[62:63], s[28:29] op_sel_hi:[1,0]
	s_nop 0
	v_fma_f32 v63, -v62, v62, v63
	v_add_f32_e32 v63, 0x3727c5ac, v63
	v_rsq_f32_e32 v254, v63
	s_waitcnt vmcnt(3)
	v_sub_f32_e32 v55, v55, v62
	v_sub_f32_e32 v54, v54, v62
	v_sub_f32_e32 v53, v53, v62
	v_sub_f32_e32 v52, v52, v62
	s_waitcnt vmcnt(2)
	v_sub_f32_e32 v59, v59, v62
	v_sub_f32_e32 v58, v58, v62
	v_sub_f32_e32 v57, v57, v62
	v_sub_f32_e32 v56, v56, v62
	s_nop 0
	s_nop 1
	v_mov_b32_e32 v64, v254
	v_pk_mul_f32 v[52:53], v[52:53], v[64:65] op_sel_hi:[1,0]
	v_pk_mul_f32 v[54:55], v[54:55], v[64:65] op_sel_hi:[1,0]
	v_pk_mul_f32 v[56:57], v[56:57], v[64:65] op_sel_hi:[1,0]
	v_pk_mul_f32 v[58:59], v[58:59], v[64:65] op_sel_hi:[1,0]
	v_pk_fma_f32 v[18:19], v[30:31], v[54:55], v[18:19]
	v_pk_fma_f32 v[16:17], v[28:29], v[52:53], v[16:17]
	v_pk_fma_f32 v[22:23], v[22:23], v[58:59], v[26:27]
	v_pk_fma_f32 v[20:21], v[20:21], v[56:57], v[24:25]
	v_pk_mul_f32 v[16:17], v[16:17], s[30:31] op_sel_hi:[1,0]
	v_pk_mul_f32 v[18:19], v[18:19], s[30:31] op_sel_hi:[1,0]
	v_pk_mul_f32 v[20:21], v[20:21], s[30:31] op_sel_hi:[1,0]
	v_pk_mul_f32 v[22:23], v[22:23], s[30:31] op_sel_hi:[1,0]
	v_pk_fma_f32 v[18:19], v[46:47], s[36:37], v[18:19] op_sel_hi:[1,0,1]
	v_pk_fma_f32 v[16:17], v[44:45], s[36:37], v[16:17] op_sel_hi:[1,0,1]
	v_pk_fma_f32 v[22:23], v[42:43], s[36:37], v[22:23] op_sel_hi:[1,0,1]
	v_pk_fma_f32 v[20:21], v[40:41], s[36:37], v[20:21] op_sel_hi:[1,0,1]
	v_fmamk_f32 v24, v18, 0x41980000, v252
	v_fmamk_f32 v25, v19, 0x41980000, v252
	v_fmamk_f32 v26, v16, 0x41980000, v252
	v_fmamk_f32 v27, v17, 0x41980000, v252
	v_fmamk_f32 v28, v22, 0x41980000, v252
	v_fmamk_f32 v29, v23, 0x41980000, v252
	v_fmamk_f32 v30, v20, 0x41980000, v252
	v_fmamk_f32 v31, v21, 0x41980000, v252
	v_med3_f32 v26, v26, s32, v253
	v_med3_f32 v27, v27, s32, v253
	v_med3_f32 v24, v24, s32, v253
	v_med3_f32 v25, v25, s32, v253
	v_med3_f32 v30, v30, s32, v253
	v_med3_f32 v31, v31, s32, v253
	v_med3_f32 v28, v28, s32, v253
	v_med3_f32 v29, v29, s32, v253
	v_perm_b32 v26, v27, v26, s65
	v_perm_b32 v24, v25, v24, s66
	v_perm_b32 v25, v31, v30, s65
	v_perm_b32 v27, v29, v28, s66
	v_or_b32_e32 v24, v26, v24
	v_or_b32_e32 v25, v25, v27
	global_store_dwordx4 v[50:51], v[16:19], off nt
	global_store_dwordx4 v[50:51], v[20:23], off offset:16 nt
	global_store_dwordx2 v[60:61], v[24:25], off
	s_waitcnt vmcnt(3)
; __device__ __forceinline__ u32x2 pack8i8(const f32x4 a, const f32x4 b) { return (u32x2){pack4i8(a), pack4i8(b)}; }
; __device__ __forceinline__ unsigned pack4i8(const f32x4 t) {
;     const float M = 12582912.f; const unsigned a = __float_as_uint(__builtin_amdgcn_fmed3f(t[0], -127.f, 127.f) + M), b = __float_as_uint(__builtin_amdgcn_fmed3f(t[1], -127.f, 127.f) + M),
;     __device__ __forceinline__ void operator()(EPI_ARGS) const {
;     ...
;             for (int m = 0; m < 4; ++m) { const int row = row0 + ai * HALF + m * 16; const size_t off = (size_t)row * DM + col0;
;                 float mu = 0.f, rs = 1.f; if constexpr (RESLN) ln_stats(stin, row, mu, rs);
;                 float ss = 0.f, qq = 0.f;
; #pragma unroll
;                 for (int bj = 0; bj < 2; ++bj) { f32x4 r0 = __builtin_nontemporal_load((const f32x4*)(res + off + bj * HALF)), r1 = __builtin_nontemporal_load((const f32x4*)(res + off + bj * HALF + 4));
;                     if constexpr (RESLN) { r0 = (r0 - mu) * rs * gg[bj][0] + bb[bj][0]; r1 = (r1 - mu) * rs * gg[bj][1] + bb[bj][1]; }
;                     const f32x4 y0 = r0 * DN_ALPHA + acc[ai][bj][m][0] * ascale, y1 = r1 * DN_ALPHA + acc[ai][bj][m][1] * ascale;
;                     if constexpr (COPY != 4) { __builtin_nontemporal_store(y0, (f32x4*)(Y + off + bj * HALF)); __builtin_nontemporal_store(y1, (f32x4*)(Y + off + bj * HALF + 4)); }
;                     if constexpr (STATS) { ss += ((y0[0] + y0[1]) + (y0[2] + y0[3])) + ((y1[0] + y1[1]) + (y1[2] + y1[3]));
;                         qq += ((y0[0] * y0[0] + y0[1] * y0[1]) + (y0[2] * y0[2] + y0[3] * y0[3])) + ((y1[0] * y1[0] + y1[1] * y1[1]) + (y1[2] * y1[2] + y1[3] * y1[3])); }
;                     if constexpr (COPY == 1) *(u32x2*)((unsigned char*)copy + off + bj * HALF) = pack8fp8(y0 * cscale, y1 * cscale);
;                     if constexpr (COPY == 3) *(u32x2*)((unsigned char*)copy + off + bj * HALF) = pack8i8(y0 * cscale, y1 * cscale);
;                     if constexpr (COPY == 2 || COPY == 4) *(u32x4*)((bf16_t*)copy + off + bj * HALF) = pack8bf(y0, y1); }
;                 if constexpr (STATS) { ss += __shfl_xor(ss, 16); ss += __shfl_xor(ss, 32); qq += __shfl_xor(qq, 16); qq += __shfl_xor(qq, 32);
;                     if (fq == 0) { unsafeAtomicAdd(stout + 2 * (size_t)row, ss); unsafeAtomicAdd(stout + 2 * (size_t)row + 1, qq); } }
	s_nop 1
	v_mov_b32_e32 v24, v228
	v_mov_b32_e32 v25, v229
	v_mov_b32_e32 v26, v230
	v_mov_b32_e32 v27, v231
	v_mov_b32_e32 v28, v232
	v_mov_b32_e32 v29, v233
	v_mov_b32_e32 v30, v234
	v_mov_b32_e32 v31, v235
	v_add_f32_e32 v40, v16, v17
	v_add_f32_e32 v41, v18, v19
	v_add_f32_e32 v42, v20, v21
	v_add_f32_e32 v43, v22, v23
	v_mul_f32_e32 v17, v17, v17
	v_mul_f32_e32 v19, v19, v19
	v_mul_f32_e32 v21, v21, v21
	v_mul_f32_e32 v23, v23, v23
	v_add_f32_e32 v40, v40, v41
	v_add_f32_e32 v41, v42, v43
	v_fmac_f32_e32 v17, v16, v16
	v_fmac_f32_e32 v19, v18, v18
	v_fmac_f32_e32 v21, v20, v20
	v_fmac_f32_e32 v23, v22, v22
	v_add_f32_e32 v16, v40, v41
	v_add_f32_e32 v17, v17, v19
	v_add_f32_e32 v18, v21, v23
	v_add_f32_e32 v40, 0, v16
	v_add_f32_e32 v41, v17, v18
	v_sub_f32_e32 v17, v27, v62
	v_sub_f32_e32 v16, v26, v62
	v_sub_f32_e32 v19, v25, v62
	v_sub_f32_e32 v18, v24, v62
	v_sub_f32_e32 v21, v31, v62
	v_sub_f32_e32 v20, v30, v62
	v_sub_f32_e32 v23, v29, v62
	v_sub_f32_e32 v22, v28, v62
	v_pk_mul_f32 v[18:19], v[18:19], v[64:65] op_sel_hi:[1,0]
	v_pk_mul_f32 v[16:17], v[16:17], v[64:65] op_sel_hi:[1,0]
	v_pk_mul_f32 v[22:23], v[22:23], v[64:65] op_sel_hi:[1,0]
	v_pk_mul_f32 v[20:21], v[20:21], v[64:65] op_sel_hi:[1,0]
	v_pk_fma_f32 v[10:11], v[10:11], v[16:17], v[14:15]
	v_pk_fma_f32 v[8:9], v[8:9], v[18:19], v[12:13]
	v_pk_fma_f32 v[2:3], v[2:3], v[20:21], v[6:7]
	v_pk_fma_f32 v[0:1], v[0:1], v[22:23], v[4:5]
	v_pk_mul_f32 v[4:5], v[8:9], s[30:31] op_sel_hi:[1,0]
	v_pk_mul_f32 v[6:7], v[10:11], s[30:31] op_sel_hi:[1,0]
	v_pk_mul_f32 v[8:9], v[0:1], s[30:31] op_sel_hi:[1,0]
	v_pk_mul_f32 v[10:11], v[2:3], s[30:31] op_sel_hi:[1,0]
	v_pk_fma_f32 v[2:3], v[38:39], s[36:37], v[6:7] op_sel_hi:[1,0,1]
	v_pk_fma_f32 v[0:1], v[36:37], s[36:37], v[4:5] op_sel_hi:[1,0,1]
	v_pk_fma_f32 v[6:7], v[34:35], s[36:37], v[10:11] op_sel_hi:[1,0,1]
	v_pk_fma_f32 v[4:5], v[32:33], s[36:37], v[8:9] op_sel_hi:[1,0,1]
	v_add_f32_e32 v16, v0, v1
	v_add_f32_e32 v17, v2, v3
	v_add_f32_e32 v18, v4, v5
	v_add_f32_e32 v19, v6, v7
	v_mul_f32_e32 v20, v1, v1
	v_mul_f32_e32 v21, v3, v3
	v_mul_f32_e32 v22, v5, v5
	v_mul_f32_e32 v23, v7, v7
	global_store_dwordx4 v[50:51], v[0:3], off offset:512 nt
	global_store_dwordx4 v[50:51], v[4:7], off offset:528 nt
	v_fmamk_f32 v8, v2, 0x41980000, v252
	v_fmamk_f32 v9, v3, 0x41980000, v252
	v_fmamk_f32 v10, v0, 0x41980000, v252
	v_fmamk_f32 v11, v1, 0x41980000, v252
	v_add_f32_e32 v1, v16, v17
	v_add_f32_e32 v3, v18, v19
	v_fmac_f32_e32 v20, v0, v0
	v_fmac_f32_e32 v21, v2, v2
	v_fmac_f32_e32 v22, v4, v4
	v_fmac_f32_e32 v23, v6, v6
	v_med3_f32 v0, v10, s32, v253
	v_add_f32_e32 v1, v1, v3
	v_add_f32_e32 v3, v20, v21
	v_add_f32_e32 v10, v22, v23
	v_med3_f32 v2, v11, s32, v253
	v_add_f32_e32 v3, v3, v10
	v_add_f32_e32 v1, v1, v40
	v_add_f32_e32 v3, v41, v3
	v_perm_b32 v0, v2, v0, s65
	v_mov_b32_e32 v2, v1
	s_nop 1
	v_permlane16_swap_b32_e32 v1, v2
	v_mov_b32_e32 v10, v3
	s_nop 1
	v_permlane16_swap_b32_e32 v3, v10
	v_fmamk_f32 v14, v4, 0x41980000, v252
	v_fmamk_f32 v15, v5, 0x41980000, v252
	v_med3_f32 v4, v8, s32, v253
	v_med3_f32 v5, v9, s32, v253
	v_perm_b32 v4, v5, v4, s66
	v_or_b32_e32 v4, v0, v4
	s_waitcnt lgkmcnt(0)
	v_add_f32_e32 v0, v1, v2
	s_waitcnt lgkmcnt(0)
	v_add_f32_e32 v2, v3, v10
	v_fmamk_f32 v12, v6, 0x41980000, v252
	v_fmamk_f32 v13, v7, 0x41980000, v252
	v_mov_b32_e32 v1, v0
	s_nop 1
	v_permlane32_swap_b32_e32 v0, v1
	v_mov_b32_e32 v3, v2
	s_nop 1
	v_permlane32_swap_b32_e32 v2, v3
	v_med3_f32 v6, v14, s32, v253
	v_med3_f32 v7, v15, s32, v253
	v_med3_f32 v8, v12, s32, v253
	v_med3_f32 v9, v13, s32, v253
	v_perm_b32 v5, v7, v6, s65
	v_perm_b32 v6, v9, v8, s66
	v_or_b32_e32 v5, v5, v6
	global_store_dwordx2 v[60:61], v[4:5], off offset:128
	s_and_saveexec_b64 s[6:7], s[2:3]
	s_cbranch_execz .LBB0_3877
	v_lshl_add_u64 v[4:5], s[12:13], 0, v[48:49]
	s_waitcnt lgkmcnt(0)
	v_add_f32_e32 v0, v0, v1
	s_waitcnt lgkmcnt(0)
	v_add_f32_e32 v1, v2, v3
	global_atomic_add_f32 v[4:5], v0, off
	global_atomic_add_f32 v[4:5], v1, off offset:4

; #define PG8_STAGE(bufoff, gbase, voff) do { _Pragma("unroll") for (int _i = 0; _i < 2; ++_i) \
;         __builtin_amdgcn_global_load_lds((const unsigned*)((const char*)(gbase) + (voff)[_i]), (LAS unsigned*)(lds + (bufoff) + ldsw + _i * 8192), 16, 0, 0); } while (0)
; #define PG8_WAIT_V(n) asm volatile("s_waitcnt vmcnt(" #n ")" ::: "memory")
; #define PG8_BAR __builtin_amdgcn_s_barrier()
;     ...
;     for (int i = 0; i < 2; ++i) { int R, C; stage_rc(tid * 16 + i * 8192, R, C); const int Rb = Epi::PERM ? ((R & ~31) + perm32(R & 31)) : R;
;         voffA[i] = (unsigned)(R * K + C) * 2u; voffB[i] = (unsigned)(Rb * K + C) * 2u; }
;     const size_t kstep = (size_t)(BK * 2);
;     const size_t hstep = (size_t)HALF * K * 2;
;     const size_t tstep = 2 * hstep;
;     const unsigned ldsw = (unsigned)wid * 1024u;
;     const int aoff = lds_byte(wr * 64 + fr, fq * 8), boff = lds_byte(wc * 32 + fr, fq * 8);
;     ...
;     Unit cur, nxt; int ui = 0;
;     if (!S.next(0, cur)) return;
;     const int sc1_ = 0x7F7F7F7F; (void)sc1_;
;     f32x4 acc[2][2][4][2];
; #pragma unroll
;     for (int a = 0; a < 2; ++a)
; #pragma unroll
;         for (int b = 0; b < 2; ++b)
; #pragma unroll
;             for (int m = 0; m < 4; ++m)
; #pragma unroll
;                 for (int n = 0; n < 2; ++n) acc[a][b][m][n] = (f32x4){0.f, 0.f, 0.f, 0.f};
;     bf16x8 At[4][2], B0[2][2], B1[2][2];
;     const char* cA = (const char*)g.A + (size_t)cur.pm * tstep + (size_t)cur.kt0 * kstep; const char* cB = (const char*)g.Bt + (size_t)cur.e * g.estride + (size_t)cur.pn * tstep + (size_t)cur.kt0 * kstep;
;     PG8_STAGE(PG8_SB(0, 0), cB, voffB); PG8_STAGE(PG8_SB(0, 1), cB + hstep, voffB); PG8_STAGE(PG8_SA(0, 0), cA, voffA); PG8_STAGE(PG8_SA(0, 1), cA + hstep, voffA);
;     if (wr == 1) PG8_BAR;
;     PG8_WAIT_V(2); PG8_BAR;
;     PG8_STAGE(PG8_SB(1, 0), cB + kstep, voffB); PG8_STAGE(PG8_SA(1, 0), cA + kstep, voffA); PG8_STAGE(PG8_SB(1, 1), cB + hstep + kstep, voffB);
;     PG8_WAIT_V(6); PG8_BAR;
.LBB0_4803:
	s_add_u32 s16, s56, 0x5a000000
	s_mov_b64 s[18:19], 0x80
	s_addc_u32 s17, s57, 0
	s_add_i32 m0, s44, 0x18000
	v_lshl_add_u64 v[8:9], v[8:9], 0, s[18:19]
	s_waitcnt vmcnt(2)
	s_barrier
	global_load_lds_dwordx4 v[8:9], off
	v_lshl_add_u64 v[6:7], v[6:7], 0, s[18:19]
	s_add_i32 m0, s44, 0x1a000
	s_add_i32 s48, s44, 0x8000
	global_load_lds_dwordx4 v[6:7], off
	v_lshl_add_u64 v[2:3], v[2:3], 0, s[18:19]
	s_mov_b32 m0, s48
	s_add_i32 s49, s44, 0xa000
	global_load_lds_dwordx4 v[2:3], off
	v_lshl_add_u64 v[2:3], v[4:5], 0, s[18:19]
	s_mov_b32 m0, s49
	s_mov_b64 s[20:21], 0xe0080
	global_load_lds_dwordx4 v[2:3], off
	v_lshl_add_u64 v[2:3], v[0:1], 0, s[20:21]
	s_add_i32 m0, s44, 0x1c000
	v_lshl_add_u64 v[4:5], v[2:3], 0, v[160:161]
	global_load_lds_dwordx4 v[4:5], off
	v_lshl_add_u64 v[2:3], v[2:3], 0, v[166:167]
	s_add_i32 m0, s44, 0x1e000
	s_mov_b32 s27, 0xe000
	global_load_lds_dwordx4 v[2:3], off
	v_lshrrev_b32_e32 v3, 1, v10
	v_and_b32_e32 v3, 24, v3
	v_and_b32_e32 v2, 15, v10
	v_lshlrev_b32_e32 v4, 1, v3
	v_lshl_or_b32 v190, s4, 6, v2
	v_lshl_or_b32 v2, v2, 6, v4
	v_lshlrev_b32_e32 v4, 2, v10
	s_lshl_b32 s4, s4, 13
	v_and_b32_e32 v4, 32, v4
	v_bitop3_b32 v5, v2, s4, v4 bitop3:0xde
	s_lshl_b32 s4, s5, 5
	s_and_b32 s4, s4, 0x60
	s_lshl_b32 s5, s4, 7
	v_bitop3_b32 v191, s5, v2, v4 bitop3:0xf6
	v_or_b32_e32 v192, s4, v3
	v_lshrrev_b32_e32 v3, 1, v13
	v_mul_lo_u32 v2, v15, s26
	v_mad_u64_u32 v[2:3], s[4:5], v3, s27, v[2:3]
	v_or_b32_e32 v2, v2, v14
	v_add_lshl_u32 v168, v2, v17, 1
	v_lshrrev_b32_e32 v3, 1, v11
	v_mul_lo_u32 v2, v16, s26
	v_mad_u64_u32 v[2:3], s[4:5], v3, s27, v[2:3]
	s_waitcnt vmcnt(6)
	s_cmpk_lt_u32 s3, 0x100
	v_mov_b32_e32 v169, 0
	v_or_b32_e32 v2, v2, v12
	s_cselect_b64 s[24:25], -1, 0
	s_ashr_i32 s3, s2, 31
	v_lshl_add_u64 v[170:171], v[168:169], 0, s[20:21]
	v_add_lshl_u32 v168, v2, v18, 1
	s_add_i32 s54, 0, 0x10000
	s_add_i32 s55, 0, 0x14000
	s_mov_b32 s50, 0
	s_ashr_i32 s51, s33, 31
	v_lshl_add_u64 v[172:173], v[168:169], 0, s[20:21]
	v_mov_b64_e32 v[174:175], s[2:3]
	s_mov_b64 s[26:27], 0x100
	v_add_u32_e32 v168, s54, v191
	v_add_u32_e32 v193, s55, v191
	v_add_u32_e32 v194, 0, v5
	v_mov_b32_e32 v195, 0x7f7f7f7f
	s_mov_b32 s28, 0x3cc80000
	s_mov_b32 s58, 0xc2fe0000
	s_mov_b32 s59, 0xc0c0400
	s_mov_b32 s60, 0x4000c0c
	s_mov_b32 s61, 0x80808080
	v_mov_b32_e32 v196, 0x42fe0000
	v_mov_b32_e32 v247, 0x4b400000
	v_mov_b32_e32 v248, 0x4b40007f
	s_mov_b32 s32, 0x4b3fff81
	s_barrier
	s_branch .LBB0_4806

; __device__ __forceinline__ unsigned pack4i8(const f32x4 t) {
;     const float M = 12582912.f; const unsigned a = __float_as_uint(__builtin_amdgcn_fmed3f(t[0], -127.f, 127.f) + M), b = __float_as_uint(__builtin_amdgcn_fmed3f(t[1], -127.f, 127.f) + M),
;                    c = __float_as_uint(__builtin_amdgcn_fmed3f(t[2], -127.f, 127.f) + M), d = __float_as_uint(__builtin_amdgcn_fmed3f(t[3], -127.f, 127.f) + M);
;     return __builtin_amdgcn_perm(b, a, 0x0c0c0400u) | __builtin_amdgcn_perm(d, c, 0x04000c0cu); }
; __device__ __forceinline__ u32x2 pack8i8(const f32x4 a, const f32x4 b) { return (u32x2){pack4i8(a), pack4i8(b)}; }
;     __device__ __forceinline__ void operator()(EPI_ARGS) const {
;     ...
;             for (int m = 0; m < 4; ++m) { const size_t eo = (size_t)u.buf * bufstride + (size_t)(row0 - rowoff + ai * HALF + m * 16) * ldc + col0;
;                 if (f8 < 0.f) { const float s8 = ascale * -f8;
; #pragma unroll
;                     for (int bj = 0; bj < 2; ++bj) { u32x2 w = pack8i8(acc[ai][bj][m][0] * s8, acc[ai][bj][m][1] * s8); w.x ^= 0x80808080u; w.y ^= 0x80808080u; *(u32x2*)((unsigned char*)O + eo + bj * HALF) = w; } }
.LBB0_4816:
	v_lshl_add_u32 v2, s65, 8, v190
	v_ashrrev_i32_e32 v3, 31, v2
	v_fmamk_f32 v6, v158, 0x3cc80000, v247
	v_fmamk_f32 v7, v159, 0x3cc80000, v247
	v_fmamk_f32 v8, v156, 0x3cc80000, v247
	v_fmamk_f32 v9, v157, 0x3cc80000, v247
	v_lshlrev_b64 v[4:5], 11, v[2:3]
	v_med3_f32 v3, v8, s32, v248
	v_med3_f32 v8, v9, s32, v248
	v_med3_f32 v6, v6, s32, v248
	v_med3_f32 v7, v7, s32, v248
	v_fmamk_f32 v10, v154, 0x3cc80000, v247
	v_fmamk_f32 v11, v155, 0x3cc80000, v247
	v_fmamk_f32 v12, v152, 0x3cc80000, v247
	v_fmamk_f32 v13, v153, 0x3cc80000, v247
	v_perm_b32 v3, v8, v3, s59
	v_perm_b32 v6, v7, v6, s60
	v_med3_f32 v7, v12, s32, v248
	v_med3_f32 v8, v13, s32, v248
	v_med3_f32 v9, v10, s32, v248
	v_med3_f32 v10, v11, s32, v248
	v_lshl_or_b32 v0, s64, 8, v192
	v_ashrrev_i32_e32 v1, 31, v0
	v_perm_b32 v7, v8, v7, s59
	v_perm_b32 v8, v10, v9, s60
	v_lshl_add_u64 v[4:5], s[16:17], 0, v[4:5]
	v_bitop3_b32 v6, v3, s61, v6 bitop3:0x36
	v_bitop3_b32 v7, v7, s61, v8 bitop3:0x36
	v_lshl_add_u64 v[4:5], v[4:5], 0, v[0:1]
	global_store_dwordx2 v[4:5], v[6:7], off
	v_fmamk_f32 v6, v150, 0x3cc80000, v247
	v_fmamk_f32 v7, v151, 0x3cc80000, v247
	v_fmamk_f32 v8, v148, 0x3cc80000, v247
	v_fmamk_f32 v9, v149, 0x3cc80000, v247
	v_med3_f32 v6, v6, s32, v248
	v_med3_f32 v3, v8, s32, v248
	v_med3_f32 v8, v9, s32, v248
	v_med3_f32 v7, v7, s32, v248
	v_fmamk_f32 v10, v146, 0x3cc80000, v247
	v_fmamk_f32 v11, v147, 0x3cc80000, v247
	v_fmamk_f32 v12, v144, 0x3cc80000, v247
	v_fmamk_f32 v13, v145, 0x3cc80000, v247
	v_perm_b32 v3, v8, v3, s59
	v_perm_b32 v6, v7, v6, s60
	v_med3_f32 v7, v12, s32, v248
	v_med3_f32 v8, v13, s32, v248
	v_med3_f32 v9, v10, s32, v248
	v_med3_f32 v10, v11, s32, v248
	v_perm_b32 v7, v8, v7, s59
	v_perm_b32 v8, v10, v9, s60
	v_bitop3_b32 v6, v3, s61, v6 bitop3:0x36
	v_bitop3_b32 v7, v7, s61, v8 bitop3:0x36
	global_store_dwordx2 v[4:5], v[6:7], off offset:128
	v_fmamk_f32 v6, v142, 0x3cc80000, v247
	v_fmamk_f32 v7, v143, 0x3cc80000, v247
	v_fmamk_f32 v8, v140, 0x3cc80000, v247
	v_fmamk_f32 v9, v141, 0x3cc80000, v247
	v_med3_f32 v6, v6, s32, v248
	v_med3_f32 v3, v8, s32, v248
	v_med3_f32 v8, v9, s32, v248
	v_med3_f32 v7, v7, s32, v248
	v_or_b32_e32 v4, 16, v2
	v_fmamk_f32 v10, v138, 0x3cc80000, v247
	v_fmamk_f32 v11, v139, 0x3cc80000, v247
	v_fmamk_f32 v12, v136, 0x3cc80000, v247
	v_fmamk_f32 v13, v137, 0x3cc80000, v247
	v_ashrrev_i32_e32 v5, 31, v4
	v_perm_b32 v3, v8, v3, s59
	v_perm_b32 v6, v7, v6, s60
	v_med3_f32 v7, v12, s32, v248
	v_med3_f32 v8, v13, s32, v248
	v_med3_f32 v9, v10, s32, v248
	v_med3_f32 v10, v11, s32, v248
	v_lshlrev_b64 v[4:5], 11, v[4:5]
	v_perm_b32 v7, v8, v7, s59
	v_perm_b32 v8, v10, v9, s60
	v_lshl_add_u64 v[4:5], s[16:17], 0, v[4:5]
	v_bitop3_b32 v6, v3, s61, v6 bitop3:0x36
	v_bitop3_b32 v7, v7, s61, v8 bitop3:0x36
	v_lshl_add_u64 v[4:5], v[4:5], 0, v[0:1]
	global_store_dwordx2 v[4:5], v[6:7], off
	v_fmamk_f32 v6, v134, 0x3cc80000, v247
	v_fmamk_f32 v7, v135, 0x3cc80000, v247
	v_fmamk_f32 v8, v132, 0x3cc80000, v247
	v_fmamk_f32 v9, v133, 0x3cc80000, v247
	v_med3_f32 v6, v6, s32, v248
	v_med3_f32 v3, v8, s32, v248
	v_med3_f32 v8, v9, s32, v248
	v_med3_f32 v7, v7, s32, v248
	v_fmamk_f32 v10, v130, 0x3cc80000, v247
	v_fmamk_f32 v11, v131, 0x3cc80000, v247
	v_fmamk_f32 v12, v128, 0x3cc80000, v247
	v_fmamk_f32 v13, v129, 0x3cc80000, v247
	v_perm_b32 v3, v8, v3, s59
	v_perm_b32 v6, v7, v6, s60
	v_med3_f32 v7, v12, s32, v248
	v_med3_f32 v8, v13, s32, v248
	v_med3_f32 v9, v10, s32, v248
	v_med3_f32 v10, v11, s32, v248
	v_perm_b32 v7, v8, v7, s59
	v_perm_b32 v8, v10, v9, s60
	v_bitop3_b32 v6, v3, s61, v6 bitop3:0x36
	v_bitop3_b32 v7, v7, s61, v8 bitop3:0x36
	global_store_dwordx2 v[4:5], v[6:7], off offset:128
	v_fmamk_f32 v6, v126, 0x3cc80000, v247
	v_fmamk_f32 v7, v127, 0x3cc80000, v247
	v_fmamk_f32 v8, v124, 0x3cc80000, v247
	v_fmamk_f32 v9, v125, 0x3cc80000, v247
	v_med3_f32 v6, v6, s32, v248
	v_med3_f32 v3, v8, s32, v248
	v_med3_f32 v8, v9, s32, v248
	v_med3_f32 v7, v7, s32, v248
	v_or_b32_e32 v4, 32, v2
	v_fmamk_f32 v10, v122, 0x3cc80000, v247
	v_fmamk_f32 v11, v123, 0x3cc80000, v247
	v_fmamk_f32 v12, v120, 0x3cc80000, v247
	v_fmamk_f32 v13, v121, 0x3cc80000, v247
	v_ashrrev_i32_e32 v5, 31, v4
	v_perm_b32 v3, v8, v3, s59
	v_perm_b32 v6, v7, v6, s60
	v_med3_f32 v7, v12, s32, v248
	v_med3_f32 v8, v13, s32, v248
	v_med3_f32 v9, v10, s32, v248
	v_med3_f32 v10, v11, s32, v248
	v_lshlrev_b64 v[4:5], 11, v[4:5]
	v_perm_b32 v7, v8, v7, s59
	v_perm_b32 v8, v10, v9, s60
	v_lshl_add_u64 v[4:5], s[16:17], 0, v[4:5]
	v_bitop3_b32 v6, v3, s61, v6 bitop3:0x36
	v_bitop3_b32 v7, v7, s61, v8 bitop3:0x36
	v_lshl_add_u64 v[4:5], v[4:5], 0, v[0:1]
	global_store_dwordx2 v[4:5], v[6:7], off
	v_fmamk_f32 v6, v118, 0x3cc80000, v247
	v_fmamk_f32 v7, v119, 0x3cc80000, v247
	v_fmamk_f32 v8, v116, 0x3cc80000, v247
	v_fmamk_f32 v9, v117, 0x3cc80000, v247
	v_med3_f32 v6, v6, s32, v248
	v_med3_f32 v3, v8, s32, v248
	v_med3_f32 v8, v9, s32, v248
	v_med3_f32 v7, v7, s32, v248
	v_fmamk_f32 v10, v114, 0x3cc80000, v247
	v_fmamk_f32 v11, v115, 0x3cc80000, v247
	v_fmamk_f32 v12, v112, 0x3cc80000, v247
	v_fmamk_f32 v13, v113, 0x3cc80000, v247
	v_perm_b32 v3, v8, v3, s59
	v_perm_b32 v6, v7, v6, s60
	v_med3_f32 v7, v12, s32, v248
	v_med3_f32 v8, v13, s32, v248
	v_med3_f32 v9, v10, s32, v248
	v_med3_f32 v10, v11, s32, v248
	v_perm_b32 v7, v8, v7, s59
	v_perm_b32 v8, v10, v9, s60
	v_bitop3_b32 v6, v3, s61, v6 bitop3:0x36
	v_bitop3_b32 v7, v7, s61, v8 bitop3:0x36
	global_store_dwordx2 v[4:5], v[6:7], off offset:128
	v_fmamk_f32 v6, v110, 0x3cc80000, v247
	v_fmamk_f32 v7, v111, 0x3cc80000, v247
	v_fmamk_f32 v8, v108, 0x3cc80000, v247
	v_fmamk_f32 v9, v109, 0x3cc80000, v247
; __device__ __forceinline__ unsigned pack4i8(const f32x4 t) {
;     const float M = 12582912.f; const unsigned a = __float_as_uint(__builtin_amdgcn_fmed3f(t[0], -127.f, 127.f) + M), b = __float_as_uint(__builtin_amdgcn_fmed3f(t[1], -127.f, 127.f) + M),
;                    c = __float_as_uint(__builtin_amdgcn_fmed3f(t[2], -127.f, 127.f) + M), d = __float_as_uint(__builtin_amdgcn_fmed3f(t[3], -127.f, 127.f) + M);
;     return __builtin_amdgcn_perm(b, a, 0x0c0c0400u) | __builtin_amdgcn_perm(d, c, 0x04000c0cu); }
; __device__ __forceinline__ u32x2 pack8i8(const f32x4 a, const f32x4 b) { return (u32x2){pack4i8(a), pack4i8(b)}; }
;     __device__ __forceinline__ void operator()(EPI_ARGS) const {
;     ...
;             for (int m = 0; m < 4; ++m) { const size_t eo = (size_t)u.buf * bufstride + (size_t)(row0 - rowoff + ai * HALF + m * 16) * ldc + col0;
;                 if (f8 < 0.f) { const float s8 = ascale * -f8;
; #pragma unroll
;                     for (int bj = 0; bj < 2; ++bj) { u32x2 w = pack8i8(acc[ai][bj][m][0] * s8, acc[ai][bj][m][1] * s8); w.x ^= 0x80808080u; w.y ^= 0x80808080u; *(u32x2*)((unsigned char*)O + eo + bj * HALF) = w; } }
	v_med3_f32 v6, v6, s32, v248
	v_med3_f32 v3, v8, s32, v248
	v_med3_f32 v8, v9, s32, v248
	v_med3_f32 v7, v7, s32, v248
	v_or_b32_e32 v4, 48, v2
	v_fmamk_f32 v10, v106, 0x3cc80000, v247
	v_fmamk_f32 v11, v107, 0x3cc80000, v247
	v_fmamk_f32 v12, v104, 0x3cc80000, v247
	v_fmamk_f32 v13, v105, 0x3cc80000, v247
	v_ashrrev_i32_e32 v5, 31, v4
	v_perm_b32 v3, v8, v3, s59
	v_perm_b32 v6, v7, v6, s60
	v_med3_f32 v7, v12, s32, v248
	v_med3_f32 v8, v13, s32, v248
	v_med3_f32 v9, v10, s32, v248
	v_med3_f32 v10, v11, s32, v248
	v_lshlrev_b64 v[4:5], 11, v[4:5]
	v_perm_b32 v7, v8, v7, s59
	v_perm_b32 v8, v10, v9, s60
	v_lshl_add_u64 v[4:5], s[16:17], 0, v[4:5]
	v_bitop3_b32 v6, v3, s61, v6 bitop3:0x36
	v_bitop3_b32 v7, v7, s61, v8 bitop3:0x36
	v_lshl_add_u64 v[4:5], v[4:5], 0, v[0:1]
	global_store_dwordx2 v[4:5], v[6:7], off
	v_fmamk_f32 v6, v102, 0x3cc80000, v247
	v_fmamk_f32 v7, v103, 0x3cc80000, v247
	v_fmamk_f32 v8, v100, 0x3cc80000, v247
	v_fmamk_f32 v9, v101, 0x3cc80000, v247
	v_med3_f32 v6, v6, s32, v248
	v_med3_f32 v3, v8, s32, v248
	v_med3_f32 v8, v9, s32, v248
	v_med3_f32 v7, v7, s32, v248
	v_fmamk_f32 v10, v98, 0x3cc80000, v247
	v_fmamk_f32 v11, v99, 0x3cc80000, v247
	v_fmamk_f32 v12, v96, 0x3cc80000, v247
	v_fmamk_f32 v13, v97, 0x3cc80000, v247
	v_perm_b32 v3, v8, v3, s59
	v_perm_b32 v6, v7, v6, s60
	v_med3_f32 v7, v12, s32, v248
	v_med3_f32 v8, v13, s32, v248
	v_med3_f32 v9, v10, s32, v248
	v_med3_f32 v10, v11, s32, v248
	v_perm_b32 v7, v8, v7, s59
	v_perm_b32 v8, v10, v9, s60
	v_bitop3_b32 v6, v3, s61, v6 bitop3:0x36
	v_bitop3_b32 v7, v7, s61, v8 bitop3:0x36
	global_store_dwordx2 v[4:5], v[6:7], off offset:128
	v_fmamk_f32 v6, v94, 0x3cc80000, v247
	v_fmamk_f32 v7, v95, 0x3cc80000, v247
	v_fmamk_f32 v8, v92, 0x3cc80000, v247
	v_fmamk_f32 v9, v93, 0x3cc80000, v247
	v_med3_f32 v6, v6, s32, v248
	v_med3_f32 v3, v8, s32, v248
	v_med3_f32 v8, v9, s32, v248
	v_med3_f32 v7, v7, s32, v248
	v_add_u32_e32 v4, 0x80, v2
	v_fmamk_f32 v10, v90, 0x3cc80000, v247
	v_fmamk_f32 v11, v91, 0x3cc80000, v247
	v_fmamk_f32 v12, v88, 0x3cc80000, v247
	v_fmamk_f32 v13, v89, 0x3cc80000, v247
	v_ashrrev_i32_e32 v5, 31, v4
	v_perm_b32 v3, v8, v3, s59
	v_perm_b32 v6, v7, v6, s60
	v_med3_f32 v7, v12, s32, v248
	v_med3_f32 v8, v13, s32, v248
	v_med3_f32 v9, v10, s32, v248
	v_med3_f32 v10, v11, s32, v248
	v_lshlrev_b64 v[4:5], 11, v[4:5]
	v_perm_b32 v7, v8, v7, s59
	v_perm_b32 v8, v10, v9, s60
	v_lshl_add_u64 v[4:5], s[16:17], 0, v[4:5]
	v_bitop3_b32 v6, v3, s61, v6 bitop3:0x36
	v_bitop3_b32 v7, v7, s61, v8 bitop3:0x36
	v_lshl_add_u64 v[4:5], v[4:5], 0, v[0:1]
	global_store_dwordx2 v[4:5], v[6:7], off
	v_fmamk_f32 v6, v86, 0x3cc80000, v247
	v_fmamk_f32 v7, v87, 0x3cc80000, v247
	v_fmamk_f32 v8, v84, 0x3cc80000, v247
	v_fmamk_f32 v9, v85, 0x3cc80000, v247
	v_med3_f32 v6, v6, s32, v248
	v_med3_f32 v3, v8, s32, v248
	v_med3_f32 v8, v9, s32, v248
	v_med3_f32 v7, v7, s32, v248
	v_fmamk_f32 v10, v82, 0x3cc80000, v247
	v_fmamk_f32 v11, v83, 0x3cc80000, v247
	v_fmamk_f32 v12, v80, 0x3cc80000, v247
	v_fmamk_f32 v13, v81, 0x3cc80000, v247
	v_perm_b32 v3, v8, v3, s59
	v_perm_b32 v6, v7, v6, s60
	v_med3_f32 v7, v12, s32, v248
	v_med3_f32 v8, v13, s32, v248
	v_med3_f32 v9, v10, s32, v248
	v_med3_f32 v10, v11, s32, v248
	v_perm_b32 v7, v8, v7, s59
	v_perm_b32 v8, v10, v9, s60
	v_bitop3_b32 v6, v3, s61, v6 bitop3:0x36
	v_bitop3_b32 v7, v7, s61, v8 bitop3:0x36
	global_store_dwordx2 v[4:5], v[6:7], off offset:128
	v_fmamk_f32 v6, v78, 0x3cc80000, v247
	v_fmamk_f32 v7, v79, 0x3cc80000, v247
	v_fmamk_f32 v8, v76, 0x3cc80000, v247
	v_fmamk_f32 v9, v77, 0x3cc80000, v247
	v_med3_f32 v6, v6, s32, v248
	v_med3_f32 v3, v8, s32, v248
	v_med3_f32 v8, v9, s32, v248
	v_med3_f32 v7, v7, s32, v248
	v_add_u32_e32 v4, 0x90, v2
	v_fmamk_f32 v10, v74, 0x3cc80000, v247
	v_fmamk_f32 v11, v75, 0x3cc80000, v247
	v_fmamk_f32 v12, v72, 0x3cc80000, v247
	v_fmamk_f32 v13, v73, 0x3cc80000, v247
	v_ashrrev_i32_e32 v5, 31, v4
	v_perm_b32 v3, v8, v3, s59
	v_perm_b32 v6, v7, v6, s60
	v_med3_f32 v7, v12, s32, v248
	v_med3_f32 v8, v13, s32, v248
	v_med3_f32 v9, v10, s32, v248
	v_med3_f32 v10, v11, s32, v248
	v_lshlrev_b64 v[4:5], 11, v[4:5]
	v_perm_b32 v7, v8, v7, s59
	v_perm_b32 v8, v10, v9, s60
	v_lshl_add_u64 v[4:5], s[16:17], 0, v[4:5]
	v_bitop3_b32 v6, v3, s61, v6 bitop3:0x36
	v_bitop3_b32 v7, v7, s61, v8 bitop3:0x36
	v_lshl_add_u64 v[4:5], v[4:5], 0, v[0:1]
	global_store_dwordx2 v[4:5], v[6:7], off
	v_fmamk_f32 v6, v70, 0x3cc80000, v247
	v_fmamk_f32 v7, v71, 0x3cc80000, v247
; __device__ __forceinline__ unsigned pack4i8(const f32x4 t) {
;     const float M = 12582912.f; const unsigned a = __float_as_uint(__builtin_amdgcn_fmed3f(t[0], -127.f, 127.f) + M), b = __float_as_uint(__builtin_amdgcn_fmed3f(t[1], -127.f, 127.f) + M),
;                    c = __float_as_uint(__builtin_amdgcn_fmed3f(t[2], -127.f, 127.f) + M), d = __float_as_uint(__builtin_amdgcn_fmed3f(t[3], -127.f, 127.f) + M);
;     return __builtin_amdgcn_perm(b, a, 0x0c0c0400u) | __builtin_amdgcn_perm(d, c, 0x04000c0cu); }
; __device__ __forceinline__ u32x2 pack8i8(const f32x4 a, const f32x4 b) { return (u32x2){pack4i8(a), pack4i8(b)}; }
;     __device__ __forceinline__ void operator()(EPI_ARGS) const {
;     ...
;             for (int m = 0; m < 4; ++m) { const size_t eo = (size_t)u.buf * bufstride + (size_t)(row0 - rowoff + ai * HALF + m * 16) * ldc + col0;
;                 if (f8 < 0.f) { const float s8 = ascale * -f8;
; #pragma unroll
;                     for (int bj = 0; bj < 2; ++bj) { u32x2 w = pack8i8(acc[ai][bj][m][0] * s8, acc[ai][bj][m][1] * s8); w.x ^= 0x80808080u; w.y ^= 0x80808080u; *(u32x2*)((unsigned char*)O + eo + bj * HALF) = w; } }
	v_fmamk_f32 v8, v68, 0x3cc80000, v247
	v_fmamk_f32 v9, v69, 0x3cc80000, v247
	v_med3_f32 v6, v6, s32, v248
	v_med3_f32 v3, v8, s32, v248
	v_med3_f32 v8, v9, s32, v248
	v_med3_f32 v7, v7, s32, v248
	v_fmamk_f32 v10, v66, 0x3cc80000, v247
	v_fmamk_f32 v11, v67, 0x3cc80000, v247
	v_fmamk_f32 v12, v64, 0x3cc80000, v247
	v_fmamk_f32 v13, v65, 0x3cc80000, v247
	v_perm_b32 v3, v8, v3, s59
	v_perm_b32 v6, v7, v6, s60
	v_med3_f32 v7, v12, s32, v248
	v_med3_f32 v8, v13, s32, v248
	v_med3_f32 v9, v10, s32, v248
	v_med3_f32 v10, v11, s32, v248
	v_perm_b32 v7, v8, v7, s59
	v_perm_b32 v8, v10, v9, s60
	v_bitop3_b32 v6, v3, s61, v6 bitop3:0x36
	v_bitop3_b32 v7, v7, s61, v8 bitop3:0x36
	global_store_dwordx2 v[4:5], v[6:7], off offset:128
	v_fmamk_f32 v6, v62, 0x3cc80000, v247
	v_fmamk_f32 v7, v63, 0x3cc80000, v247
	v_fmamk_f32 v8, v60, 0x3cc80000, v247
	v_fmamk_f32 v9, v61, 0x3cc80000, v247
	v_med3_f32 v6, v6, s32, v248
	v_med3_f32 v3, v8, s32, v248
	v_med3_f32 v8, v9, s32, v248
	v_med3_f32 v7, v7, s32, v248
	v_add_u32_e32 v4, 0xa0, v2
	v_fmamk_f32 v10, v58, 0x3cc80000, v247
	v_fmamk_f32 v11, v59, 0x3cc80000, v247
	v_fmamk_f32 v12, v56, 0x3cc80000, v247
	v_fmamk_f32 v13, v57, 0x3cc80000, v247
	v_ashrrev_i32_e32 v5, 31, v4
	v_perm_b32 v3, v8, v3, s59
	v_perm_b32 v6, v7, v6, s60
	v_med3_f32 v7, v12, s32, v248
	v_med3_f32 v8, v13, s32, v248
	v_med3_f32 v9, v10, s32, v248
	v_med3_f32 v10, v11, s32, v248
	v_lshlrev_b64 v[4:5], 11, v[4:5]
	v_perm_b32 v7, v8, v7, s59
	v_perm_b32 v8, v10, v9, s60
	v_lshl_add_u64 v[4:5], s[16:17], 0, v[4:5]
	v_bitop3_b32 v6, v3, s61, v6 bitop3:0x36
	v_bitop3_b32 v7, v7, s61, v8 bitop3:0x36
	v_lshl_add_u64 v[4:5], v[4:5], 0, v[0:1]
	global_store_dwordx2 v[4:5], v[6:7], off
	v_fmamk_f32 v6, v54, 0x3cc80000, v247
	v_fmamk_f32 v7, v55, 0x3cc80000, v247
	v_fmamk_f32 v8, v52, 0x3cc80000, v247
	v_fmamk_f32 v9, v53, 0x3cc80000, v247
	v_med3_f32 v6, v6, s32, v248
	v_med3_f32 v3, v8, s32, v248
	v_med3_f32 v8, v9, s32, v248
	v_med3_f32 v7, v7, s32, v248
	v_fmamk_f32 v10, v50, 0x3cc80000, v247
	v_fmamk_f32 v11, v51, 0x3cc80000, v247
	v_fmamk_f32 v12, v48, 0x3cc80000, v247
	v_fmamk_f32 v13, v49, 0x3cc80000, v247
	v_perm_b32 v3, v8, v3, s59
	v_perm_b32 v6, v7, v6, s60
	v_med3_f32 v7, v12, s32, v248
	v_med3_f32 v8, v13, s32, v248
	v_med3_f32 v9, v10, s32, v248
	v_med3_f32 v10, v11, s32, v248
	v_perm_b32 v7, v8, v7, s59
	v_perm_b32 v8, v10, v9, s60
	v_bitop3_b32 v6, v3, s61, v6 bitop3:0x36
	v_bitop3_b32 v7, v7, s61, v8 bitop3:0x36
	global_store_dwordx2 v[4:5], v[6:7], off offset:128
	v_fmamk_f32 v4, v46, 0x3cc80000, v247
	v_fmamk_f32 v5, v47, 0x3cc80000, v247
	v_fmamk_f32 v6, v44, 0x3cc80000, v247
	v_fmamk_f32 v7, v45, 0x3cc80000, v247
	v_med3_f32 v4, v4, s32, v248
	v_med3_f32 v6, v6, s32, v248
	v_med3_f32 v7, v7, s32, v248
	v_med3_f32 v5, v5, s32, v248
	v_add_u32_e32 v2, 0xb0, v2
	v_fmamk_f32 v8, v42, 0x3cc80000, v247
	v_fmamk_f32 v9, v43, 0x3cc80000, v247
	v_fmamk_f32 v10, v40, 0x3cc80000, v247
	v_fmamk_f32 v11, v41, 0x3cc80000, v247
	v_ashrrev_i32_e32 v3, 31, v2
	v_perm_b32 v6, v7, v6, s59
	v_perm_b32 v4, v5, v4, s60
	v_med3_f32 v5, v10, s32, v248
	v_med3_f32 v7, v11, s32, v248
	v_med3_f32 v8, v8, s32, v248
	v_med3_f32 v9, v9, s32, v248
	v_lshlrev_b64 v[2:3], 11, v[2:3]
	v_perm_b32 v5, v7, v5, s59
	v_perm_b32 v7, v9, v8, s60
	v_lshl_add_u64 v[2:3], s[16:17], 0, v[2:3]
	v_bitop3_b32 v4, v6, s61, v4 bitop3:0x36
	v_bitop3_b32 v5, v5, s61, v7 bitop3:0x36
	v_lshl_add_u64 v[0:1], v[2:3], 0, v[0:1]
	global_store_dwordx2 v[0:1], v[4:5], off
	v_fmamk_f32 v2, v38, 0x3cc80000, v247
	v_fmamk_f32 v3, v39, 0x3cc80000, v247
	v_fmamk_f32 v4, v36, 0x3cc80000, v247
	v_fmamk_f32 v5, v37, 0x3cc80000, v247
	v_med3_f32 v2, v2, s32, v248
	v_med3_f32 v4, v4, s32, v248
	v_med3_f32 v5, v5, s32, v248
	v_med3_f32 v3, v3, s32, v248
	v_fmamk_f32 v6, v34, 0x3cc80000, v247
	v_fmamk_f32 v7, v35, 0x3cc80000, v247
	v_fmamk_f32 v8, v32, 0x3cc80000, v247
	v_fmamk_f32 v9, v33, 0x3cc80000, v247
	v_perm_b32 v4, v5, v4, s59
	v_perm_b32 v2, v3, v2, s60
	v_med3_f32 v3, v8, s32, v248
	v_med3_f32 v5, v9, s32, v248
	v_med3_f32 v6, v6, s32, v248
	v_med3_f32 v7, v7, s32, v248
	v_perm_b32 v3, v5, v3, s59
	v_perm_b32 v5, v7, v6, s60
	v_bitop3_b32 v2, v4, s61, v2 bitop3:0x36
	v_bitop3_b32 v3, v3, s61, v5 bitop3:0x36
	s_and_b64 vcc, exec, s[2:3]
	s_mov_b64 s[2:3], -1
	global_store_dwordx2 v[0:1], v[2:3], off offset:128
	s_cbranch_vccnz .LBB0_4805
	s_andn2_b64 vcc, exec, s[14:15]
	s_cbranch_vccnz .LBB0_4804
	s_barrier
	s_branch .LBB0_4804
